# LRU gate sections: the 16 conv-output LDS reads hoisted to the section top (hazard nops re-derived); norm mode-1 K-tiled X stores marked nt
# speedup vs baseline: 1.0125x; 1.0019x over previous
; __device__ __forceinline__ size_t xoff(int row, int col) { return ((size_t)((row >> 8) * 32 + (col >> 6)) * 256 + (row & 255)) * 64 + (col & 63); }
; __device__ __forceinline__ void unpack8(u32x4 w, f32x4& v0, f32x4& v1) { v0 = (f32x4){bflo(w.x), bfhi(w.x), bflo(w.y), bfhi(w.y)}; v1 = (f32x4){bflo(w.z), bfhi(w.z), bflo(w.w), bfhi(w.w)}; }
; __device__ void norm_rows(const Params& p, int mode, float scale, const float* gpost) {
;     ...
;             f32x4 yv[8]; float ss = 0.f; u32x4 xw[4], yw[4]; f32x4 gq[8];
; #pragma unroll
;             for (int c = 0; c < 4; ++c) { xw[c] = *(const u32x4*)(X + xoff(row, (c * 64 + lane) * 8)); yw[c] = *(const u32x4*)(Y + (size_t)row * DM + (c * 64 + lane) * 8); }
; #pragma unroll
;             for (int c = 0; c < 4; ++c) { gq[2 * c] = *(const f32x4*)(gpost + (c * 64 + lane) * 8); gq[2 * c + 1] = *(const f32x4*)(gpost + (c * 64 + lane) * 8 + 4); }
;             asm volatile("" ::: "memory");
; #pragma unroll
;             for (int c = 0; c < 4; ++c) { unpack8(xw[c], xv[2 * c], xv[2 * c + 1]); unpack8(yw[c], yv[2 * c], yv[2 * c + 1]); }
; #pragma unroll
;             for (int c = 0; c < 8; ++c) ss += yv[c][0] * yv[c][0] + yv[c][1] * yv[c][1] + yv[c][2] * yv[c][2] + yv[c][3] * yv[c][3];
;             ss = wave_sum(ss);
;             const float rs = rsqrtf(ss * (1.0f / DM) + RMS_EPS) * scale;
.LBB0_27:
	v_ashrrev_i32_e32 v47, 31, v46
	s_waitcnt lgkmcnt(0)
	v_lshlrev_b64 v[2:3], 12, v[46:47]
	v_lshl_add_u64 v[2:3], v[58:59], 0, v[2:3]
	global_load_dwordx4 v[74:77], v[2:3], off offset:1024
	global_load_dwordx4 v[92:95], v[2:3], off offset:2048
	v_ashrrev_i32_e32 v0, 3, v46
	v_and_b32_e32 v39, 0xffffffe0, v0
	v_and_b32_e32 v4, 0x3fc0, v90
	v_or_b32_e32 v62, v39, v86
	v_lshlrev_b32_e32 v0, 1, v4
	v_ashrrev_i32_e32 v63, 31, v62
	v_lshl_add_u64 v[60:61], v[48:49], 0, v[0:1]
	v_lshlrev_b64 v[4:5], 15, v[62:63]
	v_lshl_add_u64 v[64:65], v[60:61], 0, v[4:5]
	global_load_dwordx4 v[42:45], v[2:3], off offset:3072
	global_load_dwordx4 v[34:37], v[64:65], off
	global_load_dwordx4 v[96:99], v[2:3], off
	global_load_dwordx4 v[26:29], v[50:51], off offset:16
	global_load_dwordx4 v[30:33], v[50:51], off
	global_load_dwordx4 v[18:21], v[52:53], off offset:16
	global_load_dwordx4 v[22:25], v[52:53], off
	global_load_dwordx4 v[10:13], v[54:55], off offset:16
	global_load_dwordx4 v[14:17], v[54:55], off
	global_load_dwordx4 v[2:5], v[56:57], off offset:16
	global_load_dwordx4 v[6:9], v[56:57], off
	v_or_b32_e32 v38, v39, v87
	v_or_b32_e32 v40, v39, v88
	v_or_b32_e32 v66, v39, v89
	v_ashrrev_i32_e32 v39, 31, v38
	v_lshlrev_b64 v[38:39], 15, v[38:39]
	v_ashrrev_i32_e32 v41, 31, v40
	v_lshl_add_u64 v[38:39], v[60:61], 0, v[38:39]
	v_ashrrev_i32_e32 v67, 31, v66
	global_load_dwordx4 v[100:103], v[38:39], off
	v_lshlrev_b64 v[38:39], 15, v[40:41]
	v_lshlrev_b64 v[40:41], 15, v[66:67]
	v_lshl_add_u64 v[38:39], v[60:61], 0, v[38:39]
	v_lshl_add_u64 v[40:41], v[60:61], 0, v[40:41]
	global_load_dwordx4 v[104:107], v[38:39], off
	s_nop 0
	global_load_dwordx4 v[38:41], v[40:41], off
	s_mov_b32 s0, 0x800000
	s_waitcnt vmcnt(15)
	v_and_b32_e32 v73, 0xffff0000, v74
	v_lshlrev_b32_e32 v72, 16, v74
	v_and_b32_e32 v69, 0xffff0000, v76
	v_mul_f32_e32 v0, v73, v73
	s_waitcnt vmcnt(11)
	v_and_b32_e32 v115, 0xffff0000, v96
	v_and_b32_e32 v117, 0xffff0000, v98
	v_lshlrev_b32_e32 v114, 16, v96
	v_lshlrev_b32_e32 v116, 16, v98
	v_mul_f32_e32 v91, v115, v115
	v_mul_f32_e32 v113, v117, v117
	v_lshlrev_b32_e32 v96, 16, v97
	v_lshlrev_b32_e32 v98, 16, v99
	v_fmac_f32_e32 v91, v114, v114
	v_fmac_f32_e32 v113, v116, v116
	v_lshlrev_b32_e32 v70, 16, v75
	v_lshlrev_b32_e32 v68, 16, v76
	v_and_b32_e32 v79, 0xffff0000, v92
	v_and_b32_e32 v78, 0xffff0000, v94
	v_mul_f32_e32 v63, v69, v69
	v_fmac_f32_e32 v0, v72, v72
	v_and_b32_e32 v97, 0xffff0000, v97
	v_and_b32_e32 v99, 0xffff0000, v99
	v_fmac_f32_e32 v91, v96, v96
	v_fmac_f32_e32 v113, v98, v98
	v_and_b32_e32 v71, 0xffff0000, v75
	v_lshlrev_b32_e32 v66, 16, v77
	v_lshlrev_b32_e32 v75, 16, v92
	v_lshlrev_b32_e32 v74, 16, v94
	v_pk_mul_f32 v[108:109], v[78:79], v[78:79]
	v_fmac_f32_e32 v63, v68, v68
	v_fmac_f32_e32 v0, v70, v70
	v_fmac_f32_e32 v91, v97, v97
	v_fmac_f32_e32 v113, v99, v99
	v_and_b32_e32 v67, 0xffff0000, v77
	v_lshlrev_b32_e32 v77, 16, v93
	v_lshlrev_b32_e32 v76, 16, v95
	v_pk_fma_f32 v[108:109], v[74:75], v[74:75], v[108:109]
	v_fmac_f32_e32 v63, v66, v66
	v_fmac_f32_e32 v0, v71, v71
	v_add_f32_e32 v91, v91, v113
	v_and_b32_e32 v93, 0xffff0000, v93
	v_and_b32_e32 v92, 0xffff0000, v95
	v_pk_fma_f32 v[108:109], v[76:77], v[76:77], v[108:109]
	v_fmac_f32_e32 v63, v67, v67
	v_add_f32_e32 v0, v91, v0
	v_pk_fma_f32 v[108:109], v[92:93], v[92:93], v[108:109]
	v_add_f32_e32 v0, v63, v0
	v_add_f32_e32 v0, v0, v109
	v_add_f32_e32 v0, v108, v0
	v_and_b32_e32 v109, 0xffff0000, v42
	v_and_b32_e32 v108, 0xffff0000, v44
	v_lshlrev_b32_e32 v95, 16, v42
	v_lshlrev_b32_e32 v94, 16, v44
	v_lshlrev_b32_e32 v118, 16, v45
	v_and_b32_e32 v42, 0xffff0000, v45
	v_pk_mul_f32 v[44:45], v[108:109], v[108:109]
	v_lshlrev_b32_e32 v119, 16, v43
	v_pk_fma_f32 v[44:45], v[94:95], v[94:95], v[44:45]
	v_and_b32_e32 v43, 0xffff0000, v43
	v_pk_fma_f32 v[44:45], v[118:119], v[118:119], v[44:45]
	v_lshlrev_b32_e32 v110, 16, v34
	v_pk_fma_f32 v[44:45], v[42:43], v[42:43], v[44:45]
	v_and_b32_e32 v111, 0xffff0000, v34
	v_add_f32_e32 v0, v0, v45
	v_add_f32_e32 v0, v44, v0
	ds_bpermute_b32 v45, v80, v0
	v_lshlrev_b32_e32 v34, 16, v35
	v_and_b32_e32 v35, 0xffff0000, v35
	s_waitcnt vmcnt(9)
	v_pk_mul_f32 v[32:33], v[32:33], v[96:97]
	v_lshlrev_b32_e32 v112, 16, v36
	s_waitcnt lgkmcnt(0)
	v_add_f32_e32 v0, v0, v45
	ds_bpermute_b32 v63, v81, v0
	v_and_b32_e32 v113, 0xffff0000, v36
	v_pk_mul_f32 v[30:31], v[30:31], v[114:115]
	v_pk_mul_f32 v[26:27], v[26:27], v[116:117]
	v_lshlrev_b32_e32 v36, 16, v37
	s_waitcnt lgkmcnt(0)
	v_add_f32_e32 v0, v0, v63
	ds_bpermute_b32 v63, v82, v0
	v_and_b32_e32 v37, 0xffff0000, v37
	s_waitcnt vmcnt(2)
	v_lshlrev_b32_e32 v44, 16, v100
	v_and_b32_e32 v45, 0xffff0000, v100
	v_lshlrev_b32_e32 v100, 16, v101
	s_waitcnt lgkmcnt(0)
	v_add_f32_e32 v0, v0, v63
	ds_bpermute_b32 v63, v83, v0
	v_and_b32_e32 v101, 0xffff0000, v101
	v_lshlrev_b32_e32 v120, 16, v102
	v_and_b32_e32 v121, 0xffff0000, v102
	v_lshlrev_b32_e32 v102, 16, v103
	s_waitcnt lgkmcnt(0)
	v_add_f32_e32 v0, v0, v63
	ds_bpermute_b32 v63, v84, v0
	v_and_b32_e32 v103, 0xffff0000, v103
	s_waitcnt vmcnt(1)
	v_lshlrev_b32_e32 v122, 16, v104
	v_and_b32_e32 v123, 0xffff0000, v104
	v_lshlrev_b32_e32 v104, 16, v105
	s_waitcnt lgkmcnt(0)
	v_add_f32_e32 v0, v0, v63
	ds_bpermute_b32 v63, v85, v0
	v_and_b32_e32 v105, 0xffff0000, v105
	v_lshlrev_b32_e32 v124, 16, v106
	v_and_b32_e32 v125, 0xffff0000, v106
	v_lshlrev_b32_e32 v106, 16, v107
	s_waitcnt lgkmcnt(0)
	v_add_f32_e32 v0, v0, v63
	v_fmamk_f32 v0, v0, 0x3a000000, v223
	v_mul_f32_e32 v63, 0x4b800000, v0
	v_cmp_gt_f32_e64 s[36:37], s0, v0
	v_and_b32_e32 v107, 0xffff0000, v107
	s_waitcnt vmcnt(0)
; __device__ __forceinline__ size_t xoff(int row, int col) { return ((size_t)((row >> 8) * 32 + (col >> 6)) * 256 + (row & 255)) * 64 + (col & 63); }
; __device__ __forceinline__ u32x4 pack8(f32x4 v0, f32x4 v1) { u32x4 w; w.x = cvt_pk_bf16(v0[0], v0[1]); w.y = cvt_pk_bf16(v0[2], v0[3]); w.z = cvt_pk_bf16(v1[0], v1[1]); w.w = cvt_pk_bf16(v1[2], v1[3]); return w; }
; __device__ void norm_rows(const Params& p, int mode, float scale, const float* gpost) {
;     ...
;             for (int c = 0; c < 4; ++c) { xv[2 * c] += yv[2 * c] * gq[2 * c] * rs; xv[2 * c + 1] += yv[2 * c + 1] * gq[2 * c + 1] * rs; }
;         }
;         if (mode == 2) {
; #pragma unroll
;             for (int c = 0; c < 4; ++c) { *(f32x4*)(p.out + (size_t)row * DM + (c * 64 + lane) * 8) = xv[2 * c]; *(f32x4*)(p.out + (size_t)row * DM + (c * 64 + lane) * 8 + 4) = xv[2 * c + 1]; }
;         } else {
;             float ss = 0.f;
; #pragma unroll
;             for (int c = 0; c < 8; ++c) ss += xv[c][0] * xv[c][0] + xv[c][1] * xv[c][1] + xv[c][2] * xv[c][2] + xv[c][3] * xv[c][3];
;             ss = wave_sum(ss);
; #pragma unroll
;             for (int c = 0; c < 4; ++c) *(u32x4*)(X + xoff(row, (c * 64 + lane) * 8)) = pack8(xv[2 * c], xv[2 * c + 1]);
;             if (lane == 0) RS[row] = rsqrtf(ss * (1.0f / DM) + RMS_EPS);
	v_lshlrev_b32_e32 v126, 16, v38
	v_cndmask_b32_e64 v0, v0, v63, s[36:37]
	v_rsq_f32_e32 v0, v0
	v_and_b32_e32 v127, 0xffff0000, v38
	v_lshlrev_b32_e32 v38, 16, v39
	v_and_b32_e32 v39, 0xffff0000, v39
	v_mul_f32_e32 v63, 0x45800000, v0
	v_cndmask_b32_e64 v0, v0, v63, s[36:37]
	v_pk_fma_f32 v[32:33], v[32:33], v[0:1], v[34:35] op_sel_hi:[1,0,1]
	v_mov_b32_e32 v34, v75
	v_mov_b32_e32 v35, v79
	v_pk_mul_f32 v[14:15], v[14:15], v[34:35]
	v_mov_b32_e32 v34, v77
	v_mov_b32_e32 v35, v93
	v_pk_mul_f32 v[16:17], v[16:17], v[34:35]
	v_mov_b32_e32 v34, v95
	v_mov_b32_e32 v35, v109
	v_mov_b32_e32 v75, v78
	v_mov_b32_e32 v77, v92
	v_pk_mul_f32 v[6:7], v[6:7], v[34:35]
	v_mov_b32_e32 v34, v119
	v_mov_b32_e32 v35, v43
	v_mov_b32_e32 v95, v108
	v_mov_b32_e32 v119, v42
	v_lshlrev_b32_e32 v128, 16, v40
	v_and_b32_e32 v129, 0xffff0000, v40
	v_lshlrev_b32_e32 v40, 16, v41
	v_and_b32_e32 v41, 0xffff0000, v41
	v_pk_fma_f32 v[30:31], v[30:31], v[0:1], v[110:111] op_sel_hi:[1,0,1]
	v_pk_mul_f32 v[28:29], v[28:29], v[98:99]
	v_pk_fma_f32 v[26:27], v[26:27], v[0:1], v[112:113] op_sel_hi:[1,0,1]
	v_pk_mul_f32 v[22:23], v[22:23], v[72:73]
	v_pk_mul_f32 v[24:25], v[24:25], v[70:71]
	v_pk_mul_f32 v[18:19], v[18:19], v[68:69]
	v_pk_mul_f32 v[20:21], v[20:21], v[66:67]
	v_pk_mul_f32 v[10:11], v[10:11], v[74:75]
	v_pk_mul_f32 v[12:13], v[12:13], v[76:77]
	v_pk_mul_f32 v[8:9], v[8:9], v[34:35]
	v_pk_mul_f32 v[2:3], v[2:3], v[94:95]
	v_pk_mul_f32 v[4:5], v[4:5], v[118:119]
	v_pk_fma_f32 v[28:29], v[28:29], v[0:1], v[36:37] op_sel_hi:[1,0,1]
	v_pk_fma_f32 v[24:25], v[24:25], v[0:1], v[100:101] op_sel_hi:[1,0,1]
	v_pk_fma_f32 v[22:23], v[22:23], v[0:1], v[44:45] op_sel_hi:[1,0,1]
	v_pk_fma_f32 v[20:21], v[20:21], v[0:1], v[102:103] op_sel_hi:[1,0,1]
	v_pk_fma_f32 v[18:19], v[18:19], v[0:1], v[120:121] op_sel_hi:[1,0,1]
	v_pk_fma_f32 v[16:17], v[16:17], v[0:1], v[104:105] op_sel_hi:[1,0,1]
	v_pk_fma_f32 v[14:15], v[14:15], v[0:1], v[122:123] op_sel_hi:[1,0,1]
	v_pk_fma_f32 v[12:13], v[12:13], v[0:1], v[106:107] op_sel_hi:[1,0,1]
	v_pk_fma_f32 v[10:11], v[10:11], v[0:1], v[124:125] op_sel_hi:[1,0,1]
	v_pk_fma_f32 v[8:9], v[8:9], v[0:1], v[38:39] op_sel_hi:[1,0,1]
	v_pk_fma_f32 v[34:35], v[6:7], v[0:1], v[126:127] op_sel_hi:[1,0,1]
	v_pk_fma_f32 v[36:37], v[4:5], v[0:1], v[40:41] op_sel_hi:[1,0,1]
	v_pk_fma_f32 v[38:39], v[2:3], v[0:1], v[128:129] op_sel_hi:[1,0,1]
	v_mul_f32_e32 v0, v31, v31
	v_mul_f32_e32 v2, v27, v27
	v_fmac_f32_e32 v0, v30, v30
	v_fmac_f32_e32 v2, v26, v26
	v_fmac_f32_e32 v0, v32, v32
	v_fmac_f32_e32 v2, v28, v28
	v_fmac_f32_e32 v0, v33, v33
	v_fmac_f32_e32 v2, v29, v29
	v_add_f32_e32 v0, v0, v2
	v_mul_f32_e32 v2, v23, v23
	v_fmac_f32_e32 v2, v22, v22
	v_fmac_f32_e32 v2, v24, v24
	v_fmac_f32_e32 v2, v25, v25
	v_add_f32_e32 v0, v2, v0
	v_mul_f32_e32 v2, v19, v19
	v_fmac_f32_e32 v2, v18, v18
	v_fmac_f32_e32 v2, v20, v20
	v_fmac_f32_e32 v2, v21, v21
	v_add_f32_e32 v0, v2, v0
	v_mul_f32_e32 v2, v15, v15
	v_fmac_f32_e32 v2, v14, v14
	v_fmac_f32_e32 v2, v16, v16
	v_fmac_f32_e32 v2, v17, v17
	v_add_f32_e32 v0, v2, v0
	v_mul_f32_e32 v2, v11, v11
	v_fmac_f32_e32 v2, v10, v10
	v_fmac_f32_e32 v2, v12, v12
	v_fmac_f32_e32 v2, v13, v13
	v_add_f32_e32 v0, v2, v0
	v_mul_f32_e32 v2, v35, v35
	v_fmac_f32_e32 v2, v34, v34
	v_fmac_f32_e32 v2, v8, v8
	v_fmac_f32_e32 v2, v9, v9
	v_add_f32_e32 v0, v2, v0
	v_mul_f32_e32 v2, v39, v39
	v_fmac_f32_e32 v2, v38, v38
	v_fmac_f32_e32 v2, v36, v36
	v_fmac_f32_e32 v2, v37, v37
	v_add_f32_e32 v0, v2, v0
	ds_bpermute_b32 v2, v80, v0
	v_cvt_pk_bf16_f32 v6, v26, v27
	v_cvt_pk_bf16_f32 v4, v30, v31
	v_cvt_pk_bf16_f32 v5, v32, v33
	v_cvt_pk_bf16_f32 v7, v28, v29
	s_waitcnt lgkmcnt(0)
	v_add_f32_e32 v0, v0, v2
	ds_bpermute_b32 v2, v81, v0
	global_store_dwordx4 v[64:65], v[4:7], off nt
	s_waitcnt lgkmcnt(0)
	v_add_f32_e32 v0, v0, v2
	ds_bpermute_b32 v2, v82, v0
	v_cvt_pk_bf16_f32 v6, v18, v19
	v_or_b32_e32 v18, 8, v62
	v_ashrrev_i32_e32 v19, 31, v18
	v_lshlrev_b64 v[18:19], 15, v[18:19]
	s_waitcnt lgkmcnt(0)
	v_add_f32_e32 v0, v0, v2
	ds_bpermute_b32 v2, v83, v0
	v_lshl_add_u64 v[18:19], v[60:61], 0, v[18:19]
	v_cvt_pk_bf16_f32 v4, v22, v23
	v_cvt_pk_bf16_f32 v5, v24, v25
	v_cvt_pk_bf16_f32 v7, v20, v21
	s_waitcnt lgkmcnt(0)
	v_add_f32_e32 v0, v0, v2
	ds_bpermute_b32 v2, v84, v0
	global_store_dwordx4 v[18:19], v[4:7], off nt
	s_waitcnt lgkmcnt(0)
	v_add_f32_e32 v0, v0, v2
	v_cvt_pk_bf16_f32 v6, v10, v11
	v_or_b32_e32 v10, 16, v62
	v_ashrrev_i32_e32 v11, 31, v10
	v_lshlrev_b64 v[10:11], 15, v[10:11]
	ds_bpermute_b32 v2, v85, v0
	v_cvt_pk_bf16_f32 v5, v16, v17
	v_lshl_add_u64 v[10:11], v[60:61], 0, v[10:11]
	v_cvt_pk_bf16_f32 v4, v14, v15
	v_cvt_pk_bf16_f32 v7, v12, v13
	global_store_dwordx4 v[10:11], v[4:7], off nt
	s_nop 1
	v_cvt_pk_bf16_f32 v5, v8, v9
	v_or_b32_e32 v8, 24, v62
	v_ashrrev_i32_e32 v9, 31, v8
	v_lshlrev_b64 v[8:9], 15, v[8:9]
	v_lshl_add_u64 v[8:9], v[60:61], 0, v[8:9]
	v_cvt_pk_bf16_f32 v4, v34, v35
	v_cvt_pk_bf16_f32 v6, v38, v39
	v_cvt_pk_bf16_f32 v7, v36, v37
	global_store_dwordx4 v[8:9], v[4:7], off nt
	s_and_saveexec_b64 s[0:1], vcc
	s_cbranch_execz .LBB0_26
	s_waitcnt lgkmcnt(0)
	v_add_f32_e32 v0, v0, v2
	v_fmamk_f32 v0, v0, 0x3a000000, v223
	s_mov_b32 s2, 0x800000
	v_mul_f32_e32 v2, 0x4b800000, v0
	v_cmp_gt_f32_e64 s[36:37], s2, v0
	v_readlane_b32 s2, v254, 22
	v_readlane_b32 s3, v254, 23
	v_cndmask_b32_e64 v0, v0, v2, s[36:37]
	v_rsq_f32_e32 v0, v0
	s_nop 0
	v_mul_f32_e32 v2, 0x45800000, v0
	v_cndmask_b32_e64 v0, v0, v2, s[36:37]
	v_lshl_add_u64 v[2:3], v[46:47], 2, s[2:3]
	global_store_dword v[2:3], v0, off
	s_branch .LBB0_26

; __device__ __forceinline__ bf16_t f2bf(float f) { return (bf16_t)(cvt_pk_bf16(f, 0.f) & 0xffffu); }
; __device__ __forceinline__ float bf2f(bf16_t b) { return __uint_as_float(((unsigned)b) << 16); }
; __device__ __forceinline__ float sigm(float x) { return __builtin_amdgcn_rcpf(1.0f + __expf(-x)); }
; template <int PASS>
; __device__ void lru_items(const Params& p, unsigned char* shm, int l) {
;     ...
;         { const int j = tid & 63;
; #pragma unroll
;           for (int i = 0; i < 8; ++i) { const int t = (tid >> 6) + 8 * i;
;               const float v = cb + bf2f(xraw[t * 64 + j]) * c0 + bf2f(xraw[(t + 1) * 64 + j]) * c1 + bf2f(xraw[(t + 2) * 64 + j]) * c2 + bf2f(xraw[(t + 3) * 64 + j]) * c3;
;               xcf[t * 65 + j] = v; xcb[t * 72 + j] = f2bf(v); } }
;         __syncthreads();
;         { const int d = w >> 2, tt = w & 3;
;           const bf16x8 a0 = *(const bf16x8*)(xcb + (tt * 16 + fr) * 72 + fq * 8), a1 = *(const bf16x8*)(xcb + (tt * 16 + fr) * 72 + 32 + fq * 8);
; #pragma unroll
;           for (int jt = 0; jt < 4; ++jt) {
;               f32x4 accr = (f32x4){0.f, 0.f, 0.f, 0.f}, acci = (f32x4){0.f, 0.f, 0.f, 0.f};
;               const bf16_t* wr_ = wt + ((d * 2 + 0) * 64 + jt * 16 + fr) * 72 + fq * 8; const bf16_t* wi_ = wt + ((d * 2 + 1) * 64 + jt * 16 + fr) * 72 + fq * 8;
;               accr = __builtin_amdgcn_mfma_f32_16x16x32_bf16(a0, *(const bf16x8*)wr_, accr, 0, 0, 0);
;               accr = __builtin_amdgcn_mfma_f32_16x16x32_bf16(a1, *(const bf16x8*)(wr_ + 32), accr, 0, 0, 0);
;               acci = __builtin_amdgcn_mfma_f32_16x16x32_bf16(a0, *(const bf16x8*)wi_, acci, 0, 0, 0);
;               acci = __builtin_amdgcn_mfma_f32_16x16x32_bf16(a1, *(const bf16x8*)(wi_ + 32), acci, 0, 0, 0);
;               const int j = jt * 16 + fr;
; #pragma unroll
;               for (int i = 0; i < 4; ++i) { const int t = tt * 16 + fq * 4 + i;
;                   const float r = sigm(accr[i] + gba[jt]), ig = sigm(acci[i] + gbx[jt]), a = __expf(r * gsp[jt]);
;                   As[(d * 64 + t) * 64 + j] = a;
;                   Bs[(d * 64 + t) * 64 + j] = sqrtf(fmaxf(1.0f - a * a, 0.f)) * ig * xcf[t * 65 + j]; }
.LBB0_214:
	s_mov_b32 s0, 0xf800000
	v_lshrrev_b32_e32 v183, 6, v229
	v_and_b32_e32 v184, 63, v229
	v_lshlrev_b32_e32 v185, 10, v183
	v_lshl_add_u32 v185, v184, 1, v185
	ds_read_u16 v186, v185
	ds_read_u16 v187, v185 offset:128
	ds_read_u16 v188, v185 offset:256
	ds_read_u16 v189, v185 offset:384
	ds_read_u16 v190, v185 offset:512
	ds_read_u16 v191, v185 offset:640
	ds_read_u16 v192, v185 offset:768
	ds_read_u16 v193, v185 offset:896
	ds_read_u16 v194, v185 offset:1024
	ds_read_u16 v196, v185 offset:1152
	ds_read_u16 v197, v185 offset:1280
	v_mul_u32_u24_e32 v206, 0x820, v183
	v_lshl_add_u32 v206, v184, 2, v206
	v_mul_u32_u24_e32 v207, 0x480, v183
	v_lshl_add_u32 v207, v184, 1, v207
	s_waitcnt lgkmcnt(0)
	v_lshlrev_b32_e32 v186, 16, v186
	v_lshlrev_b32_e32 v187, 16, v187
	v_lshlrev_b32_e32 v188, 16, v188
	v_lshlrev_b32_e32 v189, 16, v189
	v_lshlrev_b32_e32 v190, 16, v190
	v_lshlrev_b32_e32 v191, 16, v191
	v_lshlrev_b32_e32 v192, 16, v192
	v_lshlrev_b32_e32 v193, 16, v193
	v_lshlrev_b32_e32 v194, 16, v194
	v_lshlrev_b32_e32 v196, 16, v196
	v_lshlrev_b32_e32 v197, 16, v197
	v_fma_f32 v198, v151, v186, v150
	v_fma_f32 v199, v151, v187, v150
	v_fma_f32 v200, v151, v188, v150
	v_fma_f32 v201, v151, v189, v150
	v_fma_f32 v202, v151, v190, v150
	v_fma_f32 v203, v151, v191, v150
	v_fma_f32 v204, v151, v192, v150
	v_fma_f32 v205, v151, v193, v150
	v_fmac_f32_e32 v198, v154, v187
	v_fmac_f32_e32 v199, v154, v188
	v_fmac_f32_e32 v200, v154, v189
	v_fmac_f32_e32 v201, v154, v190
	v_fmac_f32_e32 v202, v154, v191
	v_fmac_f32_e32 v203, v154, v192
	v_fmac_f32_e32 v204, v154, v193
	v_fmac_f32_e32 v205, v154, v194
	v_fmac_f32_e32 v198, v153, v188
	v_fmac_f32_e32 v199, v153, v189
	v_fmac_f32_e32 v200, v153, v190
	v_fmac_f32_e32 v201, v153, v191
	v_fmac_f32_e32 v202, v153, v192
	v_fmac_f32_e32 v203, v153, v193
	v_fmac_f32_e32 v204, v153, v194
	v_fmac_f32_e32 v205, v153, v196
	v_fmac_f32_e32 v198, v152, v189
	v_fmac_f32_e32 v199, v152, v190
	v_fmac_f32_e32 v200, v152, v191
	v_fmac_f32_e32 v201, v152, v192
	v_fmac_f32_e32 v202, v152, v193
	v_fmac_f32_e32 v203, v152, v194
	v_fmac_f32_e32 v204, v152, v196
	v_fmac_f32_e32 v205, v152, v197
	ds_write_b32 v206, v198 offset:8704
	ds_write_b32 v206, v199 offset:8964
	ds_write_b32 v206, v200 offset:9224
	ds_write_b32 v206, v201 offset:9484
	ds_write_b32 v206, v202 offset:9744
	ds_write_b32 v206, v203 offset:10004
	ds_write_b32 v206, v204 offset:10264
	ds_write_b32 v206, v205 offset:10524
	v_cvt_pk_bf16_f32 v186, v198, v1
	v_cvt_pk_bf16_f32 v187, v199, v1
	ds_write_b16 v207, v186 offset:25344
	v_cvt_pk_bf16_f32 v188, v200, v1
	ds_write_b16 v207, v187 offset:25488
	v_cvt_pk_bf16_f32 v189, v201, v1
	ds_write_b16 v207, v188 offset:25632
	v_cvt_pk_bf16_f32 v190, v202, v1
	ds_write_b16 v207, v189 offset:25776
	v_cvt_pk_bf16_f32 v191, v203, v1
	ds_write_b16 v207, v190 offset:25920
	v_cvt_pk_bf16_f32 v192, v204, v1
	ds_write_b16 v207, v191 offset:26064
	v_cvt_pk_bf16_f32 v193, v205, v1
	ds_write_b16 v207, v192 offset:26208
	ds_write_b16 v207, v193 offset:26352
	s_waitcnt lgkmcnt(0)
	s_barrier
	ds_read_b32 v186, v149 offset:8704
	ds_read_b32 v187, v149 offset:8964
	ds_read_b32 v188, v149 offset:9224
	ds_read_b32 v189, v149 offset:9484
	ds_read_b32 v190, v149 offset:8768
	ds_read_b32 v191, v149 offset:9028
	ds_read_b32 v192, v149 offset:9288
	ds_read_b32 v193, v149 offset:9548
	ds_read_b32 v194, v149 offset:8832
	ds_read_b32 v196, v149 offset:9092
	ds_read_b32 v197, v149 offset:9352
	ds_read_b32 v198, v149 offset:9612
	ds_read_b32 v199, v149 offset:8896
	ds_read_b32 v200, v149 offset:9156
	ds_read_b32 v201, v149 offset:9416
	ds_read_b32 v202, v149 offset:9676
	ds_read_b128 v[18:21], v47 offset:25344
	ds_read_b128 v[14:17], v47 offset:25408
	ds_read_b128 v[160:163], v72 offset:34560
	ds_read_b128 v[164:167], v72 offset:34624
	s_waitcnt lgkmcnt(1)
	v_mfma_f32_16x16x32_bf16 v[160:163], v[18:21], v[160:163], 0
	ds_read_b128 v[168:171], v73 offset:43840
	s_waitcnt lgkmcnt(1)
	v_mfma_f32_16x16x32_bf16 v[160:163], v[14:17], v[164:167], v[160:163]
	ds_read_b128 v[164:167], v73 offset:43776
	s_waitcnt lgkmcnt(0)
	v_mfma_f32_16x16x32_bf16 v[164:167], v[18:21], v[164:167], 0
	s_waitcnt vmcnt(9)
	s_nop 3
	v_fmamk_f32 v0, v160, 0xbfb8aa3b, v157
	v_exp_f32_e32 v0, v0
	v_mfma_f32_16x16x32_bf16 v[164:167], v[14:17], v[168:171], v[164:167]
	v_add_f32_e32 v0, 1.0, v0
	v_rcp_f32_e32 v0, v0
	s_nop 0
	v_mul_f32_e32 v0, v23, v0
	v_exp_f32_e32 v0, v0
	s_waitcnt vmcnt(5)
	s_nop 1
	v_fmamk_f32 v35, v164, 0xbfb8aa3b, v155
	v_exp_f32_e32 v35, v35
	v_fma_f32 v36, -v0, v0, 1.0
	v_max_f32_e32 v36, 0, v36
	ds_write_b32 v74, v0
	v_add_f32_e32 v35, 1.0, v35
	v_sqrt_f32_e32 v37, v36
	v_rcp_f32_e32 v35, v35
	v_mov_b32_e32 v0, v37
	v_fmamk_f32 v37, v161, 0xbfb8aa3b, v157
	v_exp_f32_e32 v37, v37
	s_nop 0
	v_add_f32_e32 v36, 1.0, v37
	v_rcp_f32_e32 v36, v36
	v_mul_f32_e32 v0, v35, v0
	s_waitcnt lgkmcnt(0)
	v_mul_f32_e32 v0, v186, v0
	ds_write_b32 v75, v0
	v_mul_f32_e32 v0, v23, v36
	v_exp_f32_e32 v0, v0
	v_fmamk_f32 v35, v165, 0xbfb8aa3b, v155
	v_exp_f32_e32 v35, v35
	v_fma_f32 v36, -v0, v0, 1.0
	v_max_f32_e32 v36, 0, v36
	ds_write_b32 v76, v0
	v_add_f32_e32 v35, 1.0, v35
	v_sqrt_f32_e32 v37, v36
	v_rcp_f32_e32 v35, v35
	v_mov_b32_e32 v0, v37
	v_fmamk_f32 v37, v162, 0xbfb8aa3b, v157
	v_exp_f32_e32 v37, v37
	s_nop 0
	v_add_f32_e32 v36, 1.0, v37
	v_rcp_f32_e32 v36, v36
	v_mul_f32_e32 v0, v35, v0
	v_mul_f32_e32 v0, v187, v0
	ds_write_b32 v77, v0
	v_mul_f32_e32 v0, v23, v36
	v_exp_f32_e32 v0, v0
	v_fmamk_f32 v35, v166, 0xbfb8aa3b, v155
	v_exp_f32_e32 v35, v35
	v_fma_f32 v36, -v0, v0, 1.0
	v_max_f32_e32 v36, 0, v36
	ds_write_b32 v78, v0
	v_add_f32_e32 v35, 1.0, v35
	v_sqrt_f32_e32 v37, v36
	v_rcp_f32_e32 v35, v35
	v_mov_b32_e32 v0, v37
	v_fmamk_f32 v37, v163, 0xbfb8aa3b, v157
	v_exp_f32_e32 v37, v37
	s_nop 0
	v_add_f32_e32 v36, 1.0, v37
	v_rcp_f32_e32 v36, v36
	v_mul_f32_e32 v0, v35, v0
	v_mul_f32_e32 v0, v188, v0
	ds_write_b32 v79, v0
	v_mul_f32_e32 v0, v23, v36
	v_exp_f32_e32 v0, v0
	v_fmamk_f32 v35, v167, 0xbfb8aa3b, v155
	v_exp_f32_e32 v35, v35
	v_fma_f32 v36, -v0, v0, 1.0
	v_max_f32_e32 v36, 0, v36
	ds_write_b32 v80, v0
	v_add_f32_e32 v35, 1.0, v35
	v_sqrt_f32_e32 v37, v36
	v_rcp_f32_e32 v35, v35
	v_mov_b32_e32 v0, v37
	v_mul_f32_e32 v0, v35, v0
	v_mul_f32_e32 v0, v0, v189
	ds_write_b32 v81, v0
	ds_read_b128 v[160:163], v72 offset:36864
	ds_read_b128 v[164:167], v72 offset:36928
	s_waitcnt lgkmcnt(1)
; __device__ __forceinline__ float sigm(float x) { return __builtin_amdgcn_rcpf(1.0f + __expf(-x)); }
; template <int PASS>
; __device__ void lru_items(const Params& p, unsigned char* shm, int l) {
;     ...
;           for (int jt = 0; jt < 4; ++jt) {
;               f32x4 accr = (f32x4){0.f, 0.f, 0.f, 0.f}, acci = (f32x4){0.f, 0.f, 0.f, 0.f};
;               const bf16_t* wr_ = wt + ((d * 2 + 0) * 64 + jt * 16 + fr) * 72 + fq * 8; const bf16_t* wi_ = wt + ((d * 2 + 1) * 64 + jt * 16 + fr) * 72 + fq * 8;
;               accr = __builtin_amdgcn_mfma_f32_16x16x32_bf16(a0, *(const bf16x8*)wr_, accr, 0, 0, 0);
;               accr = __builtin_amdgcn_mfma_f32_16x16x32_bf16(a1, *(const bf16x8*)(wr_ + 32), accr, 0, 0, 0);
;               acci = __builtin_amdgcn_mfma_f32_16x16x32_bf16(a0, *(const bf16x8*)wi_, acci, 0, 0, 0);
;               acci = __builtin_amdgcn_mfma_f32_16x16x32_bf16(a1, *(const bf16x8*)(wi_ + 32), acci, 0, 0, 0);
;               const int j = jt * 16 + fr;
; #pragma unroll
;               for (int i = 0; i < 4; ++i) { const int t = tt * 16 + fq * 4 + i;
;                   const float r = sigm(accr[i] + gba[jt]), ig = sigm(acci[i] + gbx[jt]), a = __expf(r * gsp[jt]);
;                   As[(d * 64 + t) * 64 + j] = a;
;                   Bs[(d * 64 + t) * 64 + j] = sqrtf(fmaxf(1.0f - a * a, 0.f)) * ig * xcf[t * 65 + j]; }
	v_mfma_f32_16x16x32_bf16 v[160:163], v[18:21], v[160:163], 0
	ds_read_b128 v[168:171], v73 offset:46144
	s_waitcnt lgkmcnt(1)
	v_mfma_f32_16x16x32_bf16 v[160:163], v[14:17], v[164:167], v[160:163]
	ds_read_b128 v[164:167], v73 offset:46080
	s_waitcnt lgkmcnt(0)
	v_mfma_f32_16x16x32_bf16 v[164:167], v[18:21], v[164:167], 0
	s_nop 4
	v_fmamk_f32 v0, v160, 0xbfb8aa3b, v158
	v_exp_f32_e32 v0, v0
	v_mfma_f32_16x16x32_bf16 v[164:167], v[14:17], v[168:171], v[164:167]
	v_add_f32_e32 v0, 1.0, v0
	v_rcp_f32_e32 v0, v0
	s_nop 0
	v_mul_f32_e32 v0, v22, v0
	v_exp_f32_e32 v0, v0
	s_waitcnt vmcnt(4)
	s_nop 1
	v_fmamk_f32 v35, v164, 0xbfb8aa3b, v156
	v_exp_f32_e32 v35, v35
	v_fma_f32 v36, -v0, v0, 1.0
	v_max_f32_e32 v36, 0, v36
	ds_write_b32 v82, v0
	v_add_f32_e32 v35, 1.0, v35
	v_sqrt_f32_e32 v37, v36
	v_rcp_f32_e32 v35, v35
	v_mov_b32_e32 v0, v37
	v_fmamk_f32 v37, v161, 0xbfb8aa3b, v158
	v_exp_f32_e32 v37, v37
	s_nop 0
	v_add_f32_e32 v36, 1.0, v37
	v_rcp_f32_e32 v36, v36
	v_mul_f32_e32 v0, v35, v0
	v_mul_f32_e32 v0, v190, v0
	ds_write_b32 v83, v0
	v_mul_f32_e32 v0, v22, v36
	v_exp_f32_e32 v0, v0
	v_fmamk_f32 v35, v165, 0xbfb8aa3b, v156
	v_exp_f32_e32 v35, v35
	v_fma_f32 v36, -v0, v0, 1.0
	v_max_f32_e32 v36, 0, v36
	ds_write_b32 v84, v0
	v_add_f32_e32 v35, 1.0, v35
	v_sqrt_f32_e32 v37, v36
	v_rcp_f32_e32 v35, v35
	v_mov_b32_e32 v0, v37
	v_fmamk_f32 v37, v162, 0xbfb8aa3b, v158
	v_exp_f32_e32 v37, v37
	s_nop 0
	v_add_f32_e32 v36, 1.0, v37
	v_rcp_f32_e32 v36, v36
	v_mul_f32_e32 v0, v35, v0
	v_mul_f32_e32 v0, v191, v0
	ds_write_b32 v85, v0
	v_mul_f32_e32 v0, v22, v36
	v_exp_f32_e32 v0, v0
	v_fmamk_f32 v35, v166, 0xbfb8aa3b, v156
	v_exp_f32_e32 v35, v35
	v_fma_f32 v36, -v0, v0, 1.0
	v_max_f32_e32 v36, 0, v36
	ds_write_b32 v86, v0
	v_add_f32_e32 v35, 1.0, v35
	v_sqrt_f32_e32 v37, v36
	v_rcp_f32_e32 v35, v35
	v_mov_b32_e32 v0, v37
	v_fmamk_f32 v37, v163, 0xbfb8aa3b, v158
	v_exp_f32_e32 v37, v37
	s_nop 0
	v_add_f32_e32 v36, 1.0, v37
	v_rcp_f32_e32 v36, v36
	v_mul_f32_e32 v0, v35, v0
	v_mul_f32_e32 v0, v192, v0
	ds_write_b32 v87, v0
	v_mul_f32_e32 v0, v22, v36
	v_exp_f32_e32 v0, v0
	v_fmamk_f32 v35, v167, 0xbfb8aa3b, v156
	v_exp_f32_e32 v35, v35
	v_fma_f32 v36, -v0, v0, 1.0
	v_max_f32_e32 v36, 0, v36
	ds_write_b32 v88, v0
	v_add_f32_e32 v35, 1.0, v35
	v_sqrt_f32_e32 v37, v36
	v_rcp_f32_e32 v35, v35
	v_mov_b32_e32 v0, v37
	v_mul_f32_e32 v0, v35, v0
	v_mul_f32_e32 v0, v0, v193
	ds_write_b32 v89, v0
	ds_read_b128 v[160:163], v72 offset:39168
	ds_read_b128 v[164:167], v72 offset:39232
	s_waitcnt lgkmcnt(1)
	v_mfma_f32_16x16x32_bf16 v[160:163], v[18:21], v[160:163], 0
	ds_read_b128 v[168:171], v73 offset:48448
	s_waitcnt lgkmcnt(1)
	v_mfma_f32_16x16x32_bf16 v[160:163], v[14:17], v[164:167], v[160:163]
	ds_read_b128 v[164:167], v73 offset:48384
	s_waitcnt lgkmcnt(0)
	v_mfma_f32_16x16x32_bf16 v[164:167], v[18:21], v[164:167], 0
	s_nop 4
	v_fmamk_f32 v0, v160, 0xbfb8aa3b, v40
	v_exp_f32_e32 v0, v0
	v_mfma_f32_16x16x32_bf16 v[164:167], v[14:17], v[168:171], v[164:167]
	v_add_f32_e32 v0, 1.0, v0
	v_rcp_f32_e32 v0, v0
	s_nop 0
	v_mul_f32_e32 v0, v25, v0
	v_exp_f32_e32 v0, v0
	s_waitcnt vmcnt(3)
	s_nop 1
	v_fmamk_f32 v35, v164, 0xbfb8aa3b, v38
	v_exp_f32_e32 v35, v35
	v_fma_f32 v36, -v0, v0, 1.0
	v_max_f32_e32 v36, 0, v36
	ds_write_b32 v90, v0
	v_add_f32_e32 v35, 1.0, v35
	v_sqrt_f32_e32 v37, v36
	v_rcp_f32_e32 v35, v35
	v_mov_b32_e32 v0, v37
	v_fmamk_f32 v37, v161, 0xbfb8aa3b, v40
	v_exp_f32_e32 v37, v37
	s_nop 0
	v_add_f32_e32 v36, 1.0, v37
	v_rcp_f32_e32 v36, v36
	v_mul_f32_e32 v0, v35, v0
	v_mul_f32_e32 v0, v194, v0
	ds_write_b32 v91, v0
	v_mul_f32_e32 v0, v25, v36
	v_exp_f32_e32 v0, v0
	v_fmamk_f32 v35, v165, 0xbfb8aa3b, v38
	v_exp_f32_e32 v35, v35
	v_fma_f32 v36, -v0, v0, 1.0
	v_max_f32_e32 v36, 0, v36
	ds_write_b32 v92, v0
	v_add_f32_e32 v35, 1.0, v35
	v_sqrt_f32_e32 v37, v36
	v_rcp_f32_e32 v35, v35
	v_mov_b32_e32 v0, v37
	v_fmamk_f32 v37, v162, 0xbfb8aa3b, v40
	v_exp_f32_e32 v37, v37
	s_nop 0
	v_add_f32_e32 v36, 1.0, v37
	v_rcp_f32_e32 v36, v36
	v_mul_f32_e32 v0, v35, v0
	v_mul_f32_e32 v0, v196, v0
	ds_write_b32 v93, v0
	v_mul_f32_e32 v0, v25, v36
	v_exp_f32_e32 v0, v0
	v_fmamk_f32 v35, v166, 0xbfb8aa3b, v38
	v_exp_f32_e32 v35, v35
	v_fma_f32 v36, -v0, v0, 1.0
	v_max_f32_e32 v36, 0, v36
	ds_write_b32 v94, v0
	v_add_f32_e32 v35, 1.0, v35
	v_sqrt_f32_e32 v37, v36
	v_rcp_f32_e32 v35, v35
	v_mov_b32_e32 v0, v37
	v_fmamk_f32 v37, v163, 0xbfb8aa3b, v40
	v_exp_f32_e32 v37, v37
	s_nop 0
	v_add_f32_e32 v36, 1.0, v37
	v_rcp_f32_e32 v36, v36
	v_mul_f32_e32 v0, v35, v0
	v_mul_f32_e32 v0, v197, v0
	ds_write_b32 v95, v0
	v_mul_f32_e32 v0, v25, v36
	v_exp_f32_e32 v0, v0
	v_fmamk_f32 v35, v167, 0xbfb8aa3b, v38
	v_exp_f32_e32 v35, v35
	v_fma_f32 v36, -v0, v0, 1.0
	v_max_f32_e32 v36, 0, v36
	ds_write_b32 v96, v0
	v_add_f32_e32 v35, 1.0, v35
	v_sqrt_f32_e32 v37, v36
	v_rcp_f32_e32 v35, v35
	v_mov_b32_e32 v0, v37
	v_mul_f32_e32 v0, v35, v0
	v_mul_f32_e32 v0, v0, v198
	ds_write_b32 v97, v0
	ds_read_b128 v[160:163], v72 offset:41472
	ds_read_b128 v[164:167], v72 offset:41536
	s_waitcnt lgkmcnt(1)
; __device__ __forceinline__ float sigm(float x) { return __builtin_amdgcn_rcpf(1.0f + __expf(-x)); }
; template <int PASS>
; __device__ void lru_items(const Params& p, unsigned char* shm, int l) {
;     ...
;           for (int jt = 0; jt < 4; ++jt) {
;               f32x4 accr = (f32x4){0.f, 0.f, 0.f, 0.f}, acci = (f32x4){0.f, 0.f, 0.f, 0.f};
;               const bf16_t* wr_ = wt + ((d * 2 + 0) * 64 + jt * 16 + fr) * 72 + fq * 8; const bf16_t* wi_ = wt + ((d * 2 + 1) * 64 + jt * 16 + fr) * 72 + fq * 8;
;               accr = __builtin_amdgcn_mfma_f32_16x16x32_bf16(a0, *(const bf16x8*)wr_, accr, 0, 0, 0);
;               accr = __builtin_amdgcn_mfma_f32_16x16x32_bf16(a1, *(const bf16x8*)(wr_ + 32), accr, 0, 0, 0);
;               acci = __builtin_amdgcn_mfma_f32_16x16x32_bf16(a0, *(const bf16x8*)wi_, acci, 0, 0, 0);
;               acci = __builtin_amdgcn_mfma_f32_16x16x32_bf16(a1, *(const bf16x8*)(wi_ + 32), acci, 0, 0, 0);
;               const int j = jt * 16 + fr;
; #pragma unroll
;               for (int i = 0; i < 4; ++i) { const int t = tt * 16 + fq * 4 + i;
;                   const float r = sigm(accr[i] + gba[jt]), ig = sigm(acci[i] + gbx[jt]), a = __expf(r * gsp[jt]);
;                   As[(d * 64 + t) * 64 + j] = a;
;                   Bs[(d * 64 + t) * 64 + j] = sqrtf(fmaxf(1.0f - a * a, 0.f)) * ig * xcf[t * 65 + j]; }
;           } }
;         __syncthreads();
;         {
;             const int seg = tid >> 7, d = (tid >> 6) & 1, j = tid & 63;
;             float h = 0.f, P = 1.f;
; #pragma unroll
;             for (int s = 0; s < 16; ++s) { const int st = seg * 16 + s, t = d ? 63 - st : st; const float a = As[(d * 64 + t) * 64 + j]; h = a * h + Bs[(d * 64 + t) * 64 + j]; P *= a; }
;             Pq[seg * 128 + (tid & 127)] = P; Hq[seg * 128 + (tid & 127)] = h;
;             __syncthreads();
;             if (PASS == 0) {
;                 if (tid < 128) { float hh = Hq[tid], PP = Pq[tid];
; #pragma unroll
;                     for (int q = 1; q < 4; ++q) { const float pq = Pq[q * 128 + tid]; hh = pq * hh + Hq[q * 128 + tid]; PP *= pq; }
;                     SA[so] = PP; SH[so] = hh; }
;             } else {
;                 float c = cin;
; #pragma unroll
;                 for (int q = 0; q < 3; ++q) if (q < seg) c = Pq[q * 128 + (tid & 127)] * c + Hq[q * 128 + (tid & 127)];
; #pragma unroll
	v_mfma_f32_16x16x32_bf16 v[160:163], v[18:21], v[160:163], 0
	ds_read_b128 v[168:171], v73 offset:50752
	s_waitcnt lgkmcnt(1)
	v_mfma_f32_16x16x32_bf16 v[160:163], v[14:17], v[164:167], v[160:163]
	ds_read_b128 v[164:167], v73 offset:50688
	s_waitcnt lgkmcnt(0)
	v_mfma_f32_16x16x32_bf16 v[18:21], v[18:21], v[164:167], 0
	s_nop 4
	v_fmamk_f32 v0, v160, 0xbfb8aa3b, v41
	v_exp_f32_e32 v0, v0
	s_nop 0
	v_mfma_f32_16x16x32_bf16 v[14:17], v[14:17], v[168:171], v[18:21]
	v_add_f32_e32 v0, 1.0, v0
	v_rcp_f32_e32 v0, v0
	s_nop 0
	v_mul_f32_e32 v0, v24, v0
	v_exp_f32_e32 v0, v0
	s_waitcnt vmcnt(2)
	s_nop 1
	v_fmamk_f32 v14, v14, 0xbfb8aa3b, v39
	v_exp_f32_e32 v14, v14
	v_fma_f32 v18, -v0, v0, 1.0
	v_max_f32_e32 v18, 0, v18
	ds_write_b32 v98, v0
	v_add_f32_e32 v14, 1.0, v14
	v_sqrt_f32_e32 v19, v18
	v_rcp_f32_e32 v14, v14
	v_mov_b32_e32 v0, v19
	v_fmamk_f32 v19, v161, 0xbfb8aa3b, v41
	v_exp_f32_e32 v19, v19
	s_nop 0
	v_add_f32_e32 v18, 1.0, v19
	v_rcp_f32_e32 v18, v18
	v_mul_f32_e32 v0, v14, v0
	v_mul_f32_e32 v0, v199, v0
	ds_write_b32 v99, v0
	v_mul_f32_e32 v0, v24, v18
	v_exp_f32_e32 v0, v0
	v_fmamk_f32 v14, v15, 0xbfb8aa3b, v39
	v_exp_f32_e32 v14, v14
	v_fma_f32 v15, -v0, v0, 1.0
	v_max_f32_e32 v15, 0, v15
	ds_write_b32 v100, v0
	v_add_f32_e32 v14, 1.0, v14
	v_sqrt_f32_e32 v18, v15
	v_rcp_f32_e32 v14, v14
	v_mov_b32_e32 v0, v18
	v_fmamk_f32 v18, v162, 0xbfb8aa3b, v41
	v_exp_f32_e32 v18, v18
	s_nop 0
	v_add_f32_e32 v15, 1.0, v18
	v_rcp_f32_e32 v15, v15
	v_mul_f32_e32 v0, v14, v0
	v_mul_f32_e32 v0, v200, v0
	ds_write_b32 v101, v0
	v_mul_f32_e32 v0, v24, v15
	v_exp_f32_e32 v0, v0
	v_fmamk_f32 v14, v16, 0xbfb8aa3b, v39
	v_exp_f32_e32 v14, v14
	v_fma_f32 v15, -v0, v0, 1.0
	v_max_f32_e32 v15, 0, v15
	ds_write_b32 v102, v0
	v_add_f32_e32 v14, 1.0, v14
	v_sqrt_f32_e32 v16, v15
	v_rcp_f32_e32 v14, v14
	v_mov_b32_e32 v0, v16
	v_fmamk_f32 v16, v163, 0xbfb8aa3b, v41
	v_exp_f32_e32 v16, v16
	s_nop 0
	v_add_f32_e32 v15, 1.0, v16
	v_rcp_f32_e32 v15, v15
	v_mul_f32_e32 v0, v14, v0
	v_mul_f32_e32 v0, v201, v0
	ds_write_b32 v103, v0
	v_mul_f32_e32 v0, v24, v15
	v_exp_f32_e32 v0, v0
	v_fmamk_f32 v14, v17, 0xbfb8aa3b, v39
	v_exp_f32_e32 v14, v14
	v_fma_f32 v15, -v0, v0, 1.0
	v_max_f32_e32 v15, 0, v15
	ds_write_b32 v104, v0
	v_add_f32_e32 v14, 1.0, v14
	v_sqrt_f32_e32 v16, v15
	v_rcp_f32_e32 v14, v14
	v_mov_b32_e32 v0, v16
	v_mul_f32_e32 v0, v14, v0
	v_mul_f32_e32 v0, v0, v202
	ds_write_b32 v105, v0
	s_waitcnt lgkmcnt(0)
	s_barrier
	ds_read_b32 v0, v51
	ds_read_b32 v14, v106
	ds_read_b32 v15, v107
	ds_read_b32 v16, v108
	ds_read_b32 v17, v109
	ds_read_b32 v18, v110
	ds_read_b32 v19, v111
	ds_read_b32 v20, v112
	s_waitcnt lgkmcnt(6)
	v_fmac_f32_e32 v14, 0, v0
	s_waitcnt lgkmcnt(4)
	v_fmac_f32_e32 v16, v14, v15
	v_mul_f32_e32 v0, v0, v15
	s_waitcnt lgkmcnt(2)
	v_fmac_f32_e32 v18, v16, v17
	v_mul_f32_e32 v0, v0, v17
	s_waitcnt lgkmcnt(0)
	v_fmac_f32_e32 v20, v18, v19
	v_mul_f32_e32 v0, v0, v19
	ds_read_b32 v14, v113
	ds_read_b32 v15, v114
	ds_read_b32 v16, v115
	ds_read_b32 v17, v116
	ds_read_b32 v18, v117
	ds_read_b32 v19, v118
	ds_read_b32 v21, v119
	ds_read_b32 v35, v120
	s_waitcnt lgkmcnt(6)
	v_fmac_f32_e32 v15, v20, v14
	v_mul_f32_e32 v0, v0, v14
	s_waitcnt lgkmcnt(4)
	v_fmac_f32_e32 v17, v15, v16
	v_mul_f32_e32 v0, v0, v16
	s_waitcnt lgkmcnt(2)
	v_fmac_f32_e32 v19, v17, v18
	v_mul_f32_e32 v0, v0, v18
	s_waitcnt lgkmcnt(0)
	v_fmac_f32_e32 v35, v19, v21
	v_mul_f32_e32 v0, v0, v21
	ds_read_b32 v14, v121
	ds_read_b32 v15, v122
	ds_read_b32 v16, v123
	ds_read_b32 v17, v124
	ds_read_b32 v18, v125
	ds_read_b32 v19, v126
	ds_read_b32 v20, v127
	ds_read_b32 v21, v128
	s_waitcnt lgkmcnt(6)
	v_fmac_f32_e32 v15, v35, v14
	v_mul_f32_e32 v0, v0, v14
	s_waitcnt lgkmcnt(4)
	v_fmac_f32_e32 v17, v15, v16
	v_mul_f32_e32 v0, v0, v16
	s_waitcnt lgkmcnt(2)
	v_fmac_f32_e32 v19, v17, v18
	v_mul_f32_e32 v0, v0, v18
	s_waitcnt lgkmcnt(0)
	v_fmac_f32_e32 v21, v19, v20
	v_mul_f32_e32 v0, v0, v20
	ds_read_b32 v14, v129
	ds_read_b32 v15, v130
	ds_read_b32 v16, v131
	ds_read_b32 v17, v132
	ds_read_b32 v18, v133
	ds_read_b32 v19, v134
	ds_read_b32 v20, v135
	ds_read_b32 v35, v136
	s_waitcnt lgkmcnt(7)
	v_mul_f32_e32 v0, v0, v14
	s_waitcnt lgkmcnt(6)
	v_fmac_f32_e32 v15, v21, v14
	s_waitcnt lgkmcnt(5)
	v_mul_f32_e32 v0, v0, v16
	s_waitcnt lgkmcnt(4)
	v_fmac_f32_e32 v17, v15, v16
	s_waitcnt lgkmcnt(3)
	v_mul_f32_e32 v0, v0, v18
	s_waitcnt lgkmcnt(2)
	v_fmac_f32_e32 v19, v17, v18
	s_waitcnt lgkmcnt(1)
	v_mul_f32_e32 v0, v0, v20
	s_waitcnt lgkmcnt(0)
	v_fmac_f32_e32 v35, v19, v20
	ds_write_b32 v48, v0
	ds_write_b32 v49, v35
	s_waitcnt lgkmcnt(0)
	s_barrier
	s_and_saveexec_b64 s[0:1], s[38:39]
	s_cbranch_execnz .LBB0_217
	s_or_b64 exec, exec, s[0:1]
	s_and_saveexec_b64 s[0:1], s[40:41]
	s_cbranch_execnz .LBB0_218

; __device__ __forceinline__ bf16_t f2bf(float f) { return (bf16_t)(cvt_pk_bf16(f, 0.f) & 0xffffu); }
; __device__ __forceinline__ float bf2f(bf16_t b) { return __uint_as_float(((unsigned)b) << 16); }
; __device__ __forceinline__ float sigm(float x) { return __builtin_amdgcn_rcpf(1.0f + __expf(-x)); }
; template <int PASS>
; __device__ void lru_items(const Params& p, unsigned char* shm, int l) {
;     ...
;         { const int j = tid & 63;
; #pragma unroll
;           for (int i = 0; i < 8; ++i) { const int t = (tid >> 6) + 8 * i;
;               const float v = cb + bf2f(xraw[t * 64 + j]) * c0 + bf2f(xraw[(t + 1) * 64 + j]) * c1 + bf2f(xraw[(t + 2) * 64 + j]) * c2 + bf2f(xraw[(t + 3) * 64 + j]) * c3;
;               xcf[t * 65 + j] = v; xcb[t * 72 + j] = f2bf(v); } }
;         __syncthreads();
;         { const int d = w >> 2, tt = w & 3;
;           const bf16x8 a0 = *(const bf16x8*)(xcb + (tt * 16 + fr) * 72 + fq * 8), a1 = *(const bf16x8*)(xcb + (tt * 16 + fr) * 72 + 32 + fq * 8);
; #pragma unroll
;           for (int jt = 0; jt < 4; ++jt) {
;               f32x4 accr = (f32x4){0.f, 0.f, 0.f, 0.f}, acci = (f32x4){0.f, 0.f, 0.f, 0.f};
;               const bf16_t* wr_ = wt + ((d * 2 + 0) * 64 + jt * 16 + fr) * 72 + fq * 8; const bf16_t* wi_ = wt + ((d * 2 + 1) * 64 + jt * 16 + fr) * 72 + fq * 8;
;               accr = __builtin_amdgcn_mfma_f32_16x16x32_bf16(a0, *(const bf16x8*)wr_, accr, 0, 0, 0);
;               accr = __builtin_amdgcn_mfma_f32_16x16x32_bf16(a1, *(const bf16x8*)(wr_ + 32), accr, 0, 0, 0);
;               acci = __builtin_amdgcn_mfma_f32_16x16x32_bf16(a0, *(const bf16x8*)wi_, acci, 0, 0, 0);
;               acci = __builtin_amdgcn_mfma_f32_16x16x32_bf16(a1, *(const bf16x8*)(wi_ + 32), acci, 0, 0, 0);
;               const int j = jt * 16 + fr;
; #pragma unroll
;               for (int i = 0; i < 4; ++i) { const int t = tt * 16 + fq * 4 + i;
;                   const float r = sigm(accr[i] + gba[jt]), ig = sigm(acci[i] + gbx[jt]), a = __expf(r * gsp[jt]);
;                   As[(d * 64 + t) * 64 + j] = a;
;                   Bs[(d * 64 + t) * 64 + j] = sqrtf(fmaxf(1.0f - a * a, 0.f)) * ig * xcf[t * 65 + j]; }
.LBB0_310:
	s_mov_b32 s0, 0xf800000
	v_lshrrev_b32_e32 v183, 6, v229
	v_and_b32_e32 v184, 63, v229
	v_lshlrev_b32_e32 v185, 10, v183
	v_lshl_add_u32 v185, v184, 1, v185
	ds_read_u16 v186, v185
	ds_read_u16 v187, v185 offset:128
	ds_read_u16 v188, v185 offset:256
	ds_read_u16 v189, v185 offset:384
	ds_read_u16 v190, v185 offset:512
	ds_read_u16 v191, v185 offset:640
	ds_read_u16 v192, v185 offset:768
	ds_read_u16 v193, v185 offset:896
	ds_read_u16 v194, v185 offset:1024
	ds_read_u16 v196, v185 offset:1152
	ds_read_u16 v197, v185 offset:1280
	v_mul_u32_u24_e32 v206, 0x820, v183
	v_lshl_add_u32 v206, v184, 2, v206
	v_mul_u32_u24_e32 v207, 0x480, v183
	v_lshl_add_u32 v207, v184, 1, v207
	s_waitcnt lgkmcnt(0)
	v_lshlrev_b32_e32 v186, 16, v186
	v_lshlrev_b32_e32 v187, 16, v187
	v_lshlrev_b32_e32 v188, 16, v188
	v_lshlrev_b32_e32 v189, 16, v189
	v_lshlrev_b32_e32 v190, 16, v190
	v_lshlrev_b32_e32 v191, 16, v191
	v_lshlrev_b32_e32 v192, 16, v192
	v_lshlrev_b32_e32 v193, 16, v193
	v_lshlrev_b32_e32 v194, 16, v194
	v_lshlrev_b32_e32 v196, 16, v196
	v_lshlrev_b32_e32 v197, 16, v197
	v_fma_f32 v198, v149, v186, v148
	v_fma_f32 v199, v149, v187, v148
	v_fma_f32 v200, v149, v188, v148
	v_fma_f32 v201, v149, v189, v148
	v_fma_f32 v202, v149, v190, v148
	v_fma_f32 v203, v149, v191, v148
	v_fma_f32 v204, v149, v192, v148
	v_fma_f32 v205, v149, v193, v148
	v_fmac_f32_e32 v198, v152, v187
	v_fmac_f32_e32 v199, v152, v188
	v_fmac_f32_e32 v200, v152, v189
	v_fmac_f32_e32 v201, v152, v190
	v_fmac_f32_e32 v202, v152, v191
	v_fmac_f32_e32 v203, v152, v192
	v_fmac_f32_e32 v204, v152, v193
	v_fmac_f32_e32 v205, v152, v194
	v_fmac_f32_e32 v198, v151, v188
	v_fmac_f32_e32 v199, v151, v189
	v_fmac_f32_e32 v200, v151, v190
	v_fmac_f32_e32 v201, v151, v191
	v_fmac_f32_e32 v202, v151, v192
	v_fmac_f32_e32 v203, v151, v193
	v_fmac_f32_e32 v204, v151, v194
	v_fmac_f32_e32 v205, v151, v196
	v_fmac_f32_e32 v198, v150, v189
	v_fmac_f32_e32 v199, v150, v190
	v_fmac_f32_e32 v200, v150, v191
	v_fmac_f32_e32 v201, v150, v192
	v_fmac_f32_e32 v202, v150, v193
	v_fmac_f32_e32 v203, v150, v194
	v_fmac_f32_e32 v204, v150, v196
	v_fmac_f32_e32 v205, v150, v197
	ds_write_b32 v206, v198 offset:8704
	ds_write_b32 v206, v199 offset:8964
	ds_write_b32 v206, v200 offset:9224
	ds_write_b32 v206, v201 offset:9484
	ds_write_b32 v206, v202 offset:9744
	ds_write_b32 v206, v203 offset:10004
	ds_write_b32 v206, v204 offset:10264
	ds_write_b32 v206, v205 offset:10524
	v_cvt_pk_bf16_f32 v186, v198, v1
	v_cvt_pk_bf16_f32 v187, v199, v1
	ds_write_b16 v207, v186 offset:25344
	v_cvt_pk_bf16_f32 v188, v200, v1
	ds_write_b16 v207, v187 offset:25488
	v_cvt_pk_bf16_f32 v189, v201, v1
	ds_write_b16 v207, v188 offset:25632
	v_cvt_pk_bf16_f32 v190, v202, v1
	ds_write_b16 v207, v189 offset:25776
	v_cvt_pk_bf16_f32 v191, v203, v1
	ds_write_b16 v207, v190 offset:25920
	v_cvt_pk_bf16_f32 v192, v204, v1
	ds_write_b16 v207, v191 offset:26064
	v_cvt_pk_bf16_f32 v193, v205, v1
	ds_write_b16 v207, v192 offset:26208
	ds_write_b16 v207, v193 offset:26352
	s_waitcnt lgkmcnt(0)
	s_barrier
	ds_read_b32 v186, v147 offset:8704
	ds_read_b32 v187, v147 offset:8964
	ds_read_b32 v188, v147 offset:9224
	ds_read_b32 v189, v147 offset:9484
	ds_read_b32 v190, v147 offset:8768
	ds_read_b32 v191, v147 offset:9028
	ds_read_b32 v192, v147 offset:9288
	ds_read_b32 v193, v147 offset:9548
	ds_read_b32 v194, v147 offset:8832
	ds_read_b32 v196, v147 offset:9092
	ds_read_b32 v197, v147 offset:9352
	ds_read_b32 v198, v147 offset:9612
	ds_read_b32 v199, v147 offset:8896
	ds_read_b32 v200, v147 offset:9156
	ds_read_b32 v201, v147 offset:9416
	ds_read_b32 v202, v147 offset:9676
	ds_read_b128 v[14:17], v44 offset:25344
	ds_read_b128 v[10:13], v44 offset:25408
	ds_read_b128 v[32:35], v67 offset:34560
	ds_read_b128 v[154:157], v67 offset:34624
	s_waitcnt lgkmcnt(1)
	v_mfma_f32_16x16x32_bf16 v[32:35], v[14:17], v[32:35], 0
	ds_read_b128 v[158:161], v68 offset:43840
	s_waitcnt lgkmcnt(1)
	v_mfma_f32_16x16x32_bf16 v[32:35], v[10:13], v[154:157], v[32:35]
	ds_read_b128 v[154:157], v68 offset:43776
	s_waitcnt lgkmcnt(0)
	v_mfma_f32_16x16x32_bf16 v[154:157], v[14:17], v[154:157], 0
	s_waitcnt vmcnt(7)
	s_nop 3
	v_fmamk_f32 v0, v32, 0xbfb8aa3b, v22
	v_exp_f32_e32 v0, v0
	v_mfma_f32_16x16x32_bf16 v[154:157], v[10:13], v[158:161], v[154:157]
	v_fmamk_f32 v33, v33, 0xbfb8aa3b, v22
	v_add_f32_e32 v0, 1.0, v0
	v_rcp_f32_e32 v0, v0
	v_exp_f32_e32 v33, v33
	s_waitcnt vmcnt(3)
	s_nop 2
	v_fmamk_f32 v32, v154, 0xbfb8aa3b, v38
	v_mul_f32_e32 v0, v19, v0
	v_exp_f32_e32 v0, v0
	v_exp_f32_e32 v32, v32
	v_add_f32_e32 v33, 1.0, v33
	v_rcp_f32_e32 v33, v33
	v_fma_f32 v37, -v0, v0, 1.0
	v_max_f32_e32 v37, 0, v37
	ds_write_b32 v69, v0
	v_add_f32_e32 v32, 1.0, v32
	v_sqrt_f32_e32 v41, v37
	v_rcp_f32_e32 v32, v32
	v_fmamk_f32 v34, v34, 0xbfb8aa3b, v22
	v_mov_b32_e32 v0, v41
	v_exp_f32_e32 v34, v34
	v_mul_f32_e32 v0, v32, v0
	s_waitcnt lgkmcnt(0)
	v_mul_f32_e32 v0, v186, v0
	ds_write_b32 v70, v0
	v_mul_f32_e32 v0, v19, v33
	v_exp_f32_e32 v0, v0
	v_fmamk_f32 v32, v155, 0xbfb8aa3b, v38
	v_exp_f32_e32 v32, v32
	v_fma_f32 v33, -v0, v0, 1.0
	v_max_f32_e32 v33, 0, v33
	ds_write_b32 v71, v0
	v_add_f32_e32 v32, 1.0, v32
	v_sqrt_f32_e32 v37, v33
	v_rcp_f32_e32 v32, v32
	v_mov_b32_e32 v0, v37
	v_add_f32_e32 v33, 1.0, v34
	v_rcp_f32_e32 v33, v33
	v_mul_f32_e32 v0, v32, v0
	v_mul_f32_e32 v0, v187, v0
	ds_write_b32 v72, v0
	v_mul_f32_e32 v0, v19, v33
	v_exp_f32_e32 v0, v0
	v_fmamk_f32 v32, v156, 0xbfb8aa3b, v38
	v_exp_f32_e32 v32, v32
	v_fma_f32 v33, -v0, v0, 1.0
	v_max_f32_e32 v33, 0, v33
	ds_write_b32 v73, v0
	v_add_f32_e32 v32, 1.0, v32
	v_sqrt_f32_e32 v34, v33
	v_rcp_f32_e32 v32, v32
	v_mov_b32_e32 v0, v34
	v_fmamk_f32 v34, v35, 0xbfb8aa3b, v22
	v_exp_f32_e32 v34, v34
	s_nop 0
	v_add_f32_e32 v33, 1.0, v34
	v_rcp_f32_e32 v33, v33
	v_mul_f32_e32 v0, v32, v0
	v_mul_f32_e32 v0, v188, v0
	ds_write_b32 v74, v0
	v_mul_f32_e32 v0, v19, v33
	v_exp_f32_e32 v0, v0
	v_fmamk_f32 v32, v157, 0xbfb8aa3b, v38
	v_exp_f32_e32 v32, v32
	v_fma_f32 v33, -v0, v0, 1.0
	v_max_f32_e32 v33, 0, v33
	ds_write_b32 v75, v0
	v_add_f32_e32 v32, 1.0, v32
	v_sqrt_f32_e32 v34, v33
	v_rcp_f32_e32 v32, v32
	v_mov_b32_e32 v0, v34
	v_mul_f32_e32 v0, v32, v0
	v_mul_f32_e32 v0, v0, v189
	ds_write_b32 v76, v0
	ds_read_b128 v[32:35], v67 offset:36864
	ds_read_b128 v[154:157], v67 offset:36928
	s_waitcnt lgkmcnt(1)
; __device__ __forceinline__ float sigm(float x) { return __builtin_amdgcn_rcpf(1.0f + __expf(-x)); }
; template <int PASS>
; __device__ void lru_items(const Params& p, unsigned char* shm, int l) {
;     ...
;           for (int jt = 0; jt < 4; ++jt) {
;               f32x4 accr = (f32x4){0.f, 0.f, 0.f, 0.f}, acci = (f32x4){0.f, 0.f, 0.f, 0.f};
;               const bf16_t* wr_ = wt + ((d * 2 + 0) * 64 + jt * 16 + fr) * 72 + fq * 8; const bf16_t* wi_ = wt + ((d * 2 + 1) * 64 + jt * 16 + fr) * 72 + fq * 8;
;               accr = __builtin_amdgcn_mfma_f32_16x16x32_bf16(a0, *(const bf16x8*)wr_, accr, 0, 0, 0);
;               accr = __builtin_amdgcn_mfma_f32_16x16x32_bf16(a1, *(const bf16x8*)(wr_ + 32), accr, 0, 0, 0);
;               acci = __builtin_amdgcn_mfma_f32_16x16x32_bf16(a0, *(const bf16x8*)wi_, acci, 0, 0, 0);
;               acci = __builtin_amdgcn_mfma_f32_16x16x32_bf16(a1, *(const bf16x8*)(wi_ + 32), acci, 0, 0, 0);
;               const int j = jt * 16 + fr;
; #pragma unroll
;               for (int i = 0; i < 4; ++i) { const int t = tt * 16 + fq * 4 + i;
;                   const float r = sigm(accr[i] + gba[jt]), ig = sigm(acci[i] + gbx[jt]), a = __expf(r * gsp[jt]);
;                   As[(d * 64 + t) * 64 + j] = a;
;                   Bs[(d * 64 + t) * 64 + j] = sqrtf(fmaxf(1.0f - a * a, 0.f)) * ig * xcf[t * 65 + j]; }
	v_mfma_f32_16x16x32_bf16 v[32:35], v[14:17], v[32:35], 0
	ds_read_b128 v[158:161], v68 offset:46144
	s_waitcnt lgkmcnt(1)
	v_mfma_f32_16x16x32_bf16 v[32:35], v[10:13], v[154:157], v[32:35]
	ds_read_b128 v[154:157], v68 offset:46080
	s_waitcnt lgkmcnt(0)
	v_mfma_f32_16x16x32_bf16 v[154:157], v[14:17], v[154:157], 0
	s_nop 4
	v_fmamk_f32 v0, v32, 0xbfb8aa3b, v23
	v_exp_f32_e32 v0, v0
	v_mfma_f32_16x16x32_bf16 v[154:157], v[10:13], v[158:161], v[154:157]
	v_fmamk_f32 v33, v33, 0xbfb8aa3b, v23
	v_add_f32_e32 v0, 1.0, v0
	v_rcp_f32_e32 v0, v0
	v_exp_f32_e32 v33, v33
	s_waitcnt vmcnt(2)
	s_nop 2
	v_fmamk_f32 v32, v154, 0xbfb8aa3b, v39
	v_mul_f32_e32 v0, v18, v0
	v_exp_f32_e32 v0, v0
	v_exp_f32_e32 v32, v32
	v_add_f32_e32 v33, 1.0, v33
	v_rcp_f32_e32 v33, v33
	v_fma_f32 v37, -v0, v0, 1.0
	v_max_f32_e32 v37, 0, v37
	ds_write_b32 v77, v0
	v_add_f32_e32 v32, 1.0, v32
	v_sqrt_f32_e32 v41, v37
	v_rcp_f32_e32 v32, v32
	v_fmamk_f32 v34, v34, 0xbfb8aa3b, v23
	v_mov_b32_e32 v0, v41
	v_exp_f32_e32 v34, v34
	v_mul_f32_e32 v0, v32, v0
	v_mul_f32_e32 v0, v190, v0
	ds_write_b32 v78, v0
	v_mul_f32_e32 v0, v18, v33
	v_exp_f32_e32 v0, v0
	v_fmamk_f32 v32, v155, 0xbfb8aa3b, v39
	v_exp_f32_e32 v32, v32
	v_fma_f32 v33, -v0, v0, 1.0
	v_max_f32_e32 v33, 0, v33
	ds_write_b32 v79, v0
	v_add_f32_e32 v32, 1.0, v32
	v_sqrt_f32_e32 v37, v33
	v_rcp_f32_e32 v32, v32
	v_mov_b32_e32 v0, v37
	v_add_f32_e32 v33, 1.0, v34
	v_rcp_f32_e32 v33, v33
	v_mul_f32_e32 v0, v32, v0
	v_mul_f32_e32 v0, v191, v0
	ds_write_b32 v80, v0
	v_mul_f32_e32 v0, v18, v33
	v_exp_f32_e32 v0, v0
	v_fmamk_f32 v32, v156, 0xbfb8aa3b, v39
	v_exp_f32_e32 v32, v32
	v_fma_f32 v33, -v0, v0, 1.0
	v_max_f32_e32 v33, 0, v33
	ds_write_b32 v81, v0
	v_add_f32_e32 v32, 1.0, v32
	v_sqrt_f32_e32 v34, v33
	v_rcp_f32_e32 v32, v32
	v_mov_b32_e32 v0, v34
	v_fmamk_f32 v34, v35, 0xbfb8aa3b, v23
	v_exp_f32_e32 v34, v34
	s_nop 0
	v_add_f32_e32 v33, 1.0, v34
	v_rcp_f32_e32 v33, v33
	v_mul_f32_e32 v0, v32, v0
	v_mul_f32_e32 v0, v192, v0
	ds_write_b32 v82, v0
	v_mul_f32_e32 v0, v18, v33
	v_exp_f32_e32 v0, v0
	v_fmamk_f32 v32, v157, 0xbfb8aa3b, v39
	v_exp_f32_e32 v32, v32
	v_fma_f32 v33, -v0, v0, 1.0
	v_max_f32_e32 v33, 0, v33
	ds_write_b32 v83, v0
	v_add_f32_e32 v32, 1.0, v32
	v_sqrt_f32_e32 v34, v33
	v_rcp_f32_e32 v32, v32
	v_mov_b32_e32 v0, v34
	v_mul_f32_e32 v0, v32, v0
	v_mul_f32_e32 v0, v0, v193
	ds_write_b32 v84, v0
	ds_read_b128 v[32:35], v67 offset:39168
	ds_read_b128 v[154:157], v67 offset:39232
	s_waitcnt lgkmcnt(1)
	v_mfma_f32_16x16x32_bf16 v[32:35], v[14:17], v[32:35], 0
	ds_read_b128 v[158:161], v68 offset:48448
	s_waitcnt lgkmcnt(1)
	v_mfma_f32_16x16x32_bf16 v[32:35], v[10:13], v[154:157], v[32:35]
	ds_read_b128 v[154:157], v68 offset:48384
	s_waitcnt lgkmcnt(0)
	v_mfma_f32_16x16x32_bf16 v[154:157], v[14:17], v[154:157], 0
	s_nop 4
	v_fmamk_f32 v0, v32, 0xbfb8aa3b, v24
	v_exp_f32_e32 v0, v0
	v_mfma_f32_16x16x32_bf16 v[154:157], v[10:13], v[158:161], v[154:157]
	v_fmamk_f32 v33, v33, 0xbfb8aa3b, v24
	v_add_f32_e32 v0, 1.0, v0
	v_rcp_f32_e32 v0, v0
	v_exp_f32_e32 v33, v33
	s_waitcnt vmcnt(1)
	s_nop 2
	v_fmamk_f32 v32, v154, 0xbfb8aa3b, v40
	v_mul_f32_e32 v0, v21, v0
	v_exp_f32_e32 v0, v0
	v_exp_f32_e32 v32, v32
	v_add_f32_e32 v33, 1.0, v33
	v_rcp_f32_e32 v33, v33
	v_fma_f32 v37, -v0, v0, 1.0
	v_max_f32_e32 v37, 0, v37
	ds_write_b32 v85, v0
	v_add_f32_e32 v32, 1.0, v32
	v_sqrt_f32_e32 v41, v37
	v_rcp_f32_e32 v32, v32
	v_fmamk_f32 v34, v34, 0xbfb8aa3b, v24
	v_mov_b32_e32 v0, v41
	v_exp_f32_e32 v34, v34
	v_mul_f32_e32 v0, v32, v0
	v_mul_f32_e32 v0, v194, v0
	ds_write_b32 v86, v0
	v_mul_f32_e32 v0, v21, v33
	v_exp_f32_e32 v0, v0
	v_fmamk_f32 v32, v155, 0xbfb8aa3b, v40
	v_exp_f32_e32 v32, v32
	v_fma_f32 v33, -v0, v0, 1.0
	v_max_f32_e32 v33, 0, v33
	ds_write_b32 v87, v0
	v_add_f32_e32 v32, 1.0, v32
	v_sqrt_f32_e32 v37, v33
	v_rcp_f32_e32 v32, v32
	v_mov_b32_e32 v0, v37
	v_add_f32_e32 v33, 1.0, v34
	v_rcp_f32_e32 v33, v33
	v_mul_f32_e32 v0, v32, v0
	v_mul_f32_e32 v0, v196, v0
	ds_write_b32 v88, v0
	v_mul_f32_e32 v0, v21, v33
	v_exp_f32_e32 v0, v0
	v_fmamk_f32 v32, v156, 0xbfb8aa3b, v40
	v_exp_f32_e32 v32, v32
	v_fma_f32 v33, -v0, v0, 1.0
	v_max_f32_e32 v33, 0, v33
	ds_write_b32 v89, v0
	v_add_f32_e32 v32, 1.0, v32
	v_sqrt_f32_e32 v34, v33
	v_rcp_f32_e32 v32, v32
	v_mov_b32_e32 v0, v34
	v_fmamk_f32 v34, v35, 0xbfb8aa3b, v24
	v_exp_f32_e32 v34, v34
	s_nop 0
	v_add_f32_e32 v33, 1.0, v34
	v_rcp_f32_e32 v33, v33
	v_mul_f32_e32 v0, v32, v0
	v_mul_f32_e32 v0, v197, v0
	ds_write_b32 v90, v0
	v_mul_f32_e32 v0, v21, v33
	v_exp_f32_e32 v0, v0
	v_fmamk_f32 v32, v157, 0xbfb8aa3b, v40
	v_exp_f32_e32 v32, v32
	v_fma_f32 v33, -v0, v0, 1.0
	v_max_f32_e32 v33, 0, v33
	ds_write_b32 v91, v0
	v_add_f32_e32 v32, 1.0, v32
	v_sqrt_f32_e32 v34, v33
	v_rcp_f32_e32 v32, v32
	v_mov_b32_e32 v0, v34
	v_mul_f32_e32 v0, v32, v0
	v_mul_f32_e32 v0, v0, v198
	ds_write_b32 v92, v0
	ds_read_b128 v[32:35], v67 offset:41472
	ds_read_b128 v[154:157], v67 offset:41536
	s_waitcnt lgkmcnt(1)
	v_mfma_f32_16x16x32_bf16 v[32:35], v[14:17], v[32:35], 0
	ds_read_b128 v[158:161], v68 offset:50752
	s_waitcnt lgkmcnt(1)
	v_mfma_f32_16x16x32_bf16 v[32:35], v[10:13], v[154:157], v[32:35]
	ds_read_b128 v[154:157], v68 offset:50688
	s_waitcnt lgkmcnt(0)
; __device__ __forceinline__ float sigm(float x) { return __builtin_amdgcn_rcpf(1.0f + __expf(-x)); }
; template <int PASS>
; __device__ void lru_items(const Params& p, unsigned char* shm, int l) {
;     ...
;           for (int jt = 0; jt < 4; ++jt) {
;               f32x4 accr = (f32x4){0.f, 0.f, 0.f, 0.f}, acci = (f32x4){0.f, 0.f, 0.f, 0.f};
;               const bf16_t* wr_ = wt + ((d * 2 + 0) * 64 + jt * 16 + fr) * 72 + fq * 8; const bf16_t* wi_ = wt + ((d * 2 + 1) * 64 + jt * 16 + fr) * 72 + fq * 8;
;               accr = __builtin_amdgcn_mfma_f32_16x16x32_bf16(a0, *(const bf16x8*)wr_, accr, 0, 0, 0);
;               accr = __builtin_amdgcn_mfma_f32_16x16x32_bf16(a1, *(const bf16x8*)(wr_ + 32), accr, 0, 0, 0);
;               acci = __builtin_amdgcn_mfma_f32_16x16x32_bf16(a0, *(const bf16x8*)wi_, acci, 0, 0, 0);
;               acci = __builtin_amdgcn_mfma_f32_16x16x32_bf16(a1, *(const bf16x8*)(wi_ + 32), acci, 0, 0, 0);
;               const int j = jt * 16 + fr;
; #pragma unroll
;               for (int i = 0; i < 4; ++i) { const int t = tt * 16 + fq * 4 + i;
;                   const float r = sigm(accr[i] + gba[jt]), ig = sigm(acci[i] + gbx[jt]), a = __expf(r * gsp[jt]);
;                   As[(d * 64 + t) * 64 + j] = a;
;                   Bs[(d * 64 + t) * 64 + j] = sqrtf(fmaxf(1.0f - a * a, 0.f)) * ig * xcf[t * 65 + j]; }
;           } }
;         __syncthreads();
;         {
;             const int seg = tid >> 7, d = (tid >> 6) & 1, j = tid & 63;
;             float h = 0.f, P = 1.f;
; #pragma unroll
;             for (int s = 0; s < 16; ++s) { const int st = seg * 16 + s, t = d ? 63 - st : st; const float a = As[(d * 64 + t) * 64 + j]; h = a * h + Bs[(d * 64 + t) * 64 + j]; P *= a; }
;             Pq[seg * 128 + (tid & 127)] = P; Hq[seg * 128 + (tid & 127)] = h;
;             __syncthreads();
;             if (PASS == 0) {
;                 if (tid < 128) { float hh = Hq[tid], PP = Pq[tid];
; #pragma unroll
;                     for (int q = 1; q < 4; ++q) { const float pq = Pq[q * 128 + tid]; hh = pq * hh + Hq[q * 128 + tid]; PP *= pq; }
;                     SA[so] = PP; SH[so] = hh; }
	v_mfma_f32_16x16x32_bf16 v[14:17], v[14:17], v[154:157], 0
	s_nop 4
	v_fmamk_f32 v0, v32, 0xbfb8aa3b, v25
	v_exp_f32_e32 v0, v0
	s_nop 0
	v_mfma_f32_16x16x32_bf16 v[10:13], v[10:13], v[158:161], v[14:17]
	v_add_f32_e32 v0, 1.0, v0
	v_rcp_f32_e32 v0, v0
	s_nop 0
	v_mul_f32_e32 v0, v20, v0
	v_exp_f32_e32 v0, v0
	s_waitcnt vmcnt(0)
	s_nop 1
	v_fmamk_f32 v10, v10, 0xbfb8aa3b, v36
	v_exp_f32_e32 v10, v10
	v_fma_f32 v14, -v0, v0, 1.0
	v_max_f32_e32 v14, 0, v14
	ds_write_b32 v93, v0
	v_add_f32_e32 v10, 1.0, v10
	v_sqrt_f32_e32 v15, v14
	v_rcp_f32_e32 v10, v10
	v_mov_b32_e32 v0, v15
	v_fmamk_f32 v15, v33, 0xbfb8aa3b, v25
	v_exp_f32_e32 v15, v15
	s_nop 0
	v_add_f32_e32 v14, 1.0, v15
	v_rcp_f32_e32 v14, v14
	v_mul_f32_e32 v0, v10, v0
	v_mul_f32_e32 v0, v199, v0
	ds_write_b32 v94, v0
	v_mul_f32_e32 v0, v20, v14
	v_exp_f32_e32 v0, v0
	v_fmamk_f32 v10, v11, 0xbfb8aa3b, v36
	v_exp_f32_e32 v10, v10
	v_fma_f32 v11, -v0, v0, 1.0
	v_max_f32_e32 v11, 0, v11
	ds_write_b32 v95, v0
	v_add_f32_e32 v10, 1.0, v10
	v_sqrt_f32_e32 v14, v11
	v_rcp_f32_e32 v10, v10
	v_mov_b32_e32 v0, v14
	v_fmamk_f32 v14, v34, 0xbfb8aa3b, v25
	v_exp_f32_e32 v14, v14
	s_nop 0
	v_add_f32_e32 v11, 1.0, v14
	v_rcp_f32_e32 v11, v11
	v_mul_f32_e32 v0, v10, v0
	v_mul_f32_e32 v0, v200, v0
	ds_write_b32 v96, v0
	v_mul_f32_e32 v0, v20, v11
	v_exp_f32_e32 v0, v0
	v_fmamk_f32 v10, v12, 0xbfb8aa3b, v36
	v_exp_f32_e32 v10, v10
	v_fma_f32 v11, -v0, v0, 1.0
	v_max_f32_e32 v11, 0, v11
	ds_write_b32 v97, v0
	v_add_f32_e32 v10, 1.0, v10
	v_sqrt_f32_e32 v12, v11
	v_rcp_f32_e32 v10, v10
	v_mov_b32_e32 v0, v12
	v_fmamk_f32 v12, v35, 0xbfb8aa3b, v25
	v_exp_f32_e32 v12, v12
	s_nop 0
	v_add_f32_e32 v11, 1.0, v12
	v_rcp_f32_e32 v11, v11
	v_mul_f32_e32 v0, v10, v0
	v_mul_f32_e32 v0, v201, v0
	ds_write_b32 v98, v0
	v_mul_f32_e32 v0, v20, v11
	v_exp_f32_e32 v0, v0
	v_fmamk_f32 v10, v13, 0xbfb8aa3b, v36
	v_exp_f32_e32 v10, v10
	v_fma_f32 v11, -v0, v0, 1.0
	v_max_f32_e32 v11, 0, v11
	ds_write_b32 v99, v0
	v_add_f32_e32 v10, 1.0, v10
	v_sqrt_f32_e32 v12, v11
	v_rcp_f32_e32 v10, v10
	v_mov_b32_e32 v0, v12
	v_mul_f32_e32 v0, v10, v0
	v_mul_f32_e32 v0, v0, v202
	ds_write_b32 v100, v0
	s_waitcnt lgkmcnt(0)
	s_barrier
	ds_read_b32 v0, v101
	ds_read_b32 v10, v102
	ds_read_b32 v11, v103
	ds_read_b32 v12, v104
	ds_read_b32 v13, v105
	ds_read_b32 v14, v106
	ds_read_b32 v15, v107
	ds_read_b32 v16, v108
	s_waitcnt lgkmcnt(6)
	v_fmac_f32_e32 v10, 0, v0
	s_waitcnt lgkmcnt(4)
	v_fmac_f32_e32 v12, v10, v11
	v_mul_f32_e32 v0, v0, v11
	s_waitcnt lgkmcnt(2)
	v_fmac_f32_e32 v14, v12, v13
	v_mul_f32_e32 v0, v0, v13
	s_waitcnt lgkmcnt(0)
	v_fmac_f32_e32 v16, v14, v15
	v_mul_f32_e32 v0, v0, v15
	ds_read_b32 v10, v109
	ds_read_b32 v11, v110
	ds_read_b32 v12, v111
	ds_read_b32 v13, v112
	ds_read_b32 v14, v113
	ds_read_b32 v15, v114
	ds_read_b32 v17, v115
	ds_read_b32 v32, v116
	s_waitcnt lgkmcnt(6)
	v_fmac_f32_e32 v11, v16, v10
	v_mul_f32_e32 v0, v0, v10
	s_waitcnt lgkmcnt(4)
	v_fmac_f32_e32 v13, v11, v12
	v_mul_f32_e32 v0, v0, v12
	s_waitcnt lgkmcnt(2)
	v_fmac_f32_e32 v15, v13, v14
	v_mul_f32_e32 v0, v0, v14
	s_waitcnt lgkmcnt(0)
	v_fmac_f32_e32 v32, v15, v17
	v_mul_f32_e32 v0, v0, v17
	ds_read_b32 v10, v117
	ds_read_b32 v11, v118
	ds_read_b32 v12, v119
	ds_read_b32 v13, v120
	ds_read_b32 v14, v121
	ds_read_b32 v15, v122
	ds_read_b32 v16, v123
	ds_read_b32 v17, v124
	s_waitcnt lgkmcnt(6)
	v_fmac_f32_e32 v11, v32, v10
	v_mul_f32_e32 v0, v0, v10
	s_waitcnt lgkmcnt(4)
	v_fmac_f32_e32 v13, v11, v12
	v_mul_f32_e32 v0, v0, v12
	s_waitcnt lgkmcnt(2)
	v_fmac_f32_e32 v15, v13, v14
	v_mul_f32_e32 v0, v0, v14
	s_waitcnt lgkmcnt(0)
	v_fmac_f32_e32 v17, v15, v16
	v_mul_f32_e32 v0, v0, v16
	ds_read_b32 v10, v125
	ds_read_b32 v11, v126
	ds_read_b32 v12, v127
	ds_read_b32 v13, v128
	ds_read_b32 v14, v129
	ds_read_b32 v15, v131
	ds_read_b32 v16, v132
	ds_read_b32 v32, v133
	s_waitcnt lgkmcnt(7)
	v_mul_f32_e32 v0, v0, v10
	s_waitcnt lgkmcnt(6)
	v_fmac_f32_e32 v11, v17, v10
	s_waitcnt lgkmcnt(5)
	v_mul_f32_e32 v0, v0, v12
	s_waitcnt lgkmcnt(4)
	v_fmac_f32_e32 v13, v11, v12
	s_waitcnt lgkmcnt(3)
	v_mul_f32_e32 v0, v0, v14
	s_waitcnt lgkmcnt(2)
	v_fmac_f32_e32 v15, v13, v14
	s_waitcnt lgkmcnt(1)
	v_mul_f32_e32 v0, v0, v16
	s_waitcnt lgkmcnt(0)
	v_fmac_f32_e32 v32, v15, v16
	ds_write_b32 v45, v0
	ds_write_b32 v46, v32
	s_waitcnt lgkmcnt(0)
	s_barrier
	s_and_saveexec_b64 s[40:41], s[38:39]
	s_cbranch_execz .LBB0_295
	ds_read_b32 v0, v46
	ds_read_b32 v12, v45
	ds_read_b32 v13, v134
	ds_read_b32 v14, v135
	s_ashr_i32 s0, s2, 3
	v_and_or_b32 v10, s0, -2, v43
	v_ashrrev_i32_e32 v11, 31, v10
	s_mov_b32 s51, s49
	s_waitcnt lgkmcnt(0)
	v_fmac_f32_e32 v14, v0, v13
	v_mul_f32_e32 v0, v12, v13
	ds_read_b32 v12, v136
	ds_read_b32 v13, v137
	v_lshlrev_b64 v[10:11], 10, v[10:11]
	v_lshl_add_u64 v[10:11], v[10:11], 0, s[50:51]
	v_or_b32_e32 v10, v10, v26
	s_waitcnt lgkmcnt(1)
	v_mul_f32_e32 v0, v0, v12
	s_waitcnt lgkmcnt(0)
	v_fmac_f32_e32 v13, v14, v12
	ds_read_b32 v12, v138
	ds_read_b32 v14, v139
	v_lshlrev_b64 v[10:11], 2, v[10:11]
	s_movk_i32 s23, 0xff7f
	v_readlane_b32 s22, v254, 8
	s_movk_i32 s17, 0x84
	s_mov_b32 s15, 0xfe03f81
	s_movk_i32 s10, 0xc00
	s_waitcnt lgkmcnt(0)
	v_fmac_f32_e32 v14, v13, v12
	v_mul_f32_e32 v0, v0, v12
	v_lshl_add_u64 v[12:13], s[34:35], 0, v[10:11]
	v_lshl_add_u64 v[10:11], s[96:97], 0, v[10:11]
	global_store_dword v[12:13], v0, off
	global_store_dword v[10:11], v14, off
	s_branch .LBB0_295

; __device__ __forceinline__ size_t xoff(int row, int col) { return ((size_t)((row >> 8) * 32 + (col >> 6)) * 256 + (row & 255)) * 64 + (col & 63); }
; __device__ __forceinline__ void unpack8(u32x4 w, f32x4& v0, f32x4& v1) { v0 = (f32x4){bflo(w.x), bfhi(w.x), bflo(w.y), bfhi(w.y)}; v1 = (f32x4){bflo(w.z), bfhi(w.z), bflo(w.w), bfhi(w.w)}; }
; __device__ void norm_rows(const Params& p, int mode, float scale, const float* gpost) {
;     ...
;             f32x4 yv[8]; float ss = 0.f; u32x4 xw[4], yw[4]; f32x4 gq[8];
; #pragma unroll
;             for (int c = 0; c < 4; ++c) { xw[c] = *(const u32x4*)(X + xoff(row, (c * 64 + lane) * 8)); yw[c] = *(const u32x4*)(Y + (size_t)row * DM + (c * 64 + lane) * 8); }
; #pragma unroll
;             for (int c = 0; c < 4; ++c) { gq[2 * c] = *(const f32x4*)(gpost + (c * 64 + lane) * 8); gq[2 * c + 1] = *(const f32x4*)(gpost + (c * 64 + lane) * 8 + 4); }
;             asm volatile("" ::: "memory");
; #pragma unroll
;             for (int c = 0; c < 4; ++c) { unpack8(xw[c], xv[2 * c], xv[2 * c + 1]); unpack8(yw[c], yv[2 * c], yv[2 * c + 1]); }
; #pragma unroll
;             for (int c = 0; c < 8; ++c) ss += yv[c][0] * yv[c][0] + yv[c][1] * yv[c][1] + yv[c][2] * yv[c][2] + yv[c][3] * yv[c][3];
;             ss = wave_sum(ss);
;             const float rs = rsqrtf(ss * (1.0f / DM) + RMS_EPS) * scale;
.LBB0_787:
	v_ashrrev_i32_e32 v47, 31, v46
	s_waitcnt lgkmcnt(0)
	v_lshlrev_b64 v[2:3], 12, v[46:47]
	v_lshl_add_u64 v[2:3], v[58:59], 0, v[2:3]
	global_load_dwordx4 v[74:77], v[2:3], off offset:1024
	global_load_dwordx4 v[94:97], v[2:3], off offset:2048
	v_ashrrev_i32_e32 v0, 3, v46
	v_and_b32_e32 v39, 0xffffffe0, v0
	v_and_b32_e32 v4, 0x3fc0, v92
	v_or_b32_e32 v62, v39, v88
	v_lshlrev_b32_e32 v0, 1, v4
	v_ashrrev_i32_e32 v63, 31, v62
	v_lshl_add_u64 v[60:61], v[48:49], 0, v[0:1]
	v_lshlrev_b64 v[4:5], 15, v[62:63]
	v_lshl_add_u64 v[64:65], v[60:61], 0, v[4:5]
	global_load_dwordx4 v[42:45], v[2:3], off offset:3072
	global_load_dwordx4 v[34:37], v[64:65], off
	global_load_dwordx4 v[98:101], v[2:3], off
	global_load_dwordx4 v[26:29], v[50:51], off offset:16
	global_load_dwordx4 v[30:33], v[50:51], off
	global_load_dwordx4 v[18:21], v[52:53], off offset:16
	global_load_dwordx4 v[22:25], v[52:53], off
	global_load_dwordx4 v[10:13], v[54:55], off offset:16
	global_load_dwordx4 v[14:17], v[54:55], off
	global_load_dwordx4 v[2:5], v[56:57], off offset:16
	global_load_dwordx4 v[6:9], v[56:57], off
	v_or_b32_e32 v38, v39, v89
	v_or_b32_e32 v40, v39, v90
	v_or_b32_e32 v66, v39, v91
	v_ashrrev_i32_e32 v39, 31, v38
	v_lshlrev_b64 v[38:39], 15, v[38:39]
	v_ashrrev_i32_e32 v41, 31, v40
	v_lshl_add_u64 v[38:39], v[60:61], 0, v[38:39]
	v_ashrrev_i32_e32 v67, 31, v66
	global_load_dwordx4 v[102:105], v[38:39], off
	v_lshlrev_b64 v[38:39], 15, v[40:41]
	v_lshlrev_b64 v[40:41], 15, v[66:67]
	v_lshl_add_u64 v[38:39], v[60:61], 0, v[38:39]
	v_lshl_add_u64 v[40:41], v[60:61], 0, v[40:41]
	global_load_dwordx4 v[106:109], v[38:39], off
	s_nop 0
	global_load_dwordx4 v[38:41], v[40:41], off
	s_mov_b32 s0, 0x800000
	s_waitcnt vmcnt(15)
	v_and_b32_e32 v73, 0xffff0000, v74
	v_lshlrev_b32_e32 v72, 16, v74
	v_and_b32_e32 v69, 0xffff0000, v76
	v_mul_f32_e32 v0, v73, v73
	s_waitcnt vmcnt(11)
	v_and_b32_e32 v115, 0xffff0000, v98
	v_and_b32_e32 v117, 0xffff0000, v100
	v_lshlrev_b32_e32 v114, 16, v98
	v_lshlrev_b32_e32 v116, 16, v100
	v_mul_f32_e32 v93, v115, v115
	v_mul_f32_e32 v113, v117, v117
	v_lshlrev_b32_e32 v98, 16, v99
	v_lshlrev_b32_e32 v100, 16, v101
	v_fmac_f32_e32 v93, v114, v114
	v_fmac_f32_e32 v113, v116, v116
	v_lshlrev_b32_e32 v70, 16, v75
	v_lshlrev_b32_e32 v68, 16, v76
	v_and_b32_e32 v79, 0xffff0000, v94
	v_and_b32_e32 v78, 0xffff0000, v96
	v_mul_f32_e32 v63, v69, v69
	v_fmac_f32_e32 v0, v72, v72
	v_and_b32_e32 v99, 0xffff0000, v99
	v_and_b32_e32 v101, 0xffff0000, v101
	v_fmac_f32_e32 v93, v98, v98
	v_fmac_f32_e32 v113, v100, v100
	v_and_b32_e32 v71, 0xffff0000, v75
	v_lshlrev_b32_e32 v66, 16, v77
	v_lshlrev_b32_e32 v75, 16, v94
	v_lshlrev_b32_e32 v74, 16, v96
	v_lshlrev_b32_e32 v76, 16, v97
	v_and_b32_e32 v80, 0xffff0000, v97
	v_pk_mul_f32 v[96:97], v[78:79], v[78:79]
	v_fmac_f32_e32 v63, v68, v68
	v_fmac_f32_e32 v0, v70, v70
	v_fmac_f32_e32 v93, v99, v99
	v_fmac_f32_e32 v113, v101, v101
	v_and_b32_e32 v67, 0xffff0000, v77
	v_lshlrev_b32_e32 v77, 16, v95
	v_pk_fma_f32 v[96:97], v[74:75], v[74:75], v[96:97]
	v_fmac_f32_e32 v63, v66, v66
	v_fmac_f32_e32 v0, v71, v71
	v_add_f32_e32 v93, v93, v113
	v_and_b32_e32 v81, 0xffff0000, v95
	v_pk_fma_f32 v[96:97], v[76:77], v[76:77], v[96:97]
	v_fmac_f32_e32 v63, v67, v67
	v_add_f32_e32 v0, v93, v0
	v_pk_fma_f32 v[96:97], v[80:81], v[80:81], v[96:97]
	v_add_f32_e32 v0, v63, v0
	v_add_f32_e32 v0, v0, v97
	v_add_f32_e32 v0, v96, v0
	v_and_b32_e32 v97, 0xffff0000, v42
	v_and_b32_e32 v96, 0xffff0000, v44
	v_lshlrev_b32_e32 v95, 16, v42
	v_lshlrev_b32_e32 v94, 16, v44
	v_lshlrev_b32_e32 v118, 16, v45
	v_and_b32_e32 v42, 0xffff0000, v45
	v_pk_mul_f32 v[44:45], v[96:97], v[96:97]
	v_lshlrev_b32_e32 v119, 16, v43
	v_pk_fma_f32 v[44:45], v[94:95], v[94:95], v[44:45]
	v_and_b32_e32 v43, 0xffff0000, v43
	v_pk_fma_f32 v[44:45], v[118:119], v[118:119], v[44:45]
	v_lshlrev_b32_e32 v110, 16, v34
	v_pk_fma_f32 v[44:45], v[42:43], v[42:43], v[44:45]
	v_and_b32_e32 v111, 0xffff0000, v34
	v_add_f32_e32 v0, v0, v45
	v_add_f32_e32 v0, v44, v0
	ds_bpermute_b32 v45, v82, v0
	v_lshlrev_b32_e32 v34, 16, v35
	v_and_b32_e32 v35, 0xffff0000, v35
	s_waitcnt vmcnt(9)
	v_pk_mul_f32 v[32:33], v[32:33], v[98:99]
	v_lshlrev_b32_e32 v112, 16, v36
	s_waitcnt lgkmcnt(0)
	v_add_f32_e32 v0, v0, v45
	ds_bpermute_b32 v63, v83, v0
	v_and_b32_e32 v113, 0xffff0000, v36
	v_pk_mul_f32 v[30:31], v[30:31], v[114:115]
	v_pk_mul_f32 v[26:27], v[26:27], v[116:117]
	v_lshlrev_b32_e32 v36, 16, v37
	s_waitcnt lgkmcnt(0)
	v_add_f32_e32 v0, v0, v63
	ds_bpermute_b32 v63, v84, v0
	v_and_b32_e32 v37, 0xffff0000, v37
	s_waitcnt vmcnt(2)
	v_lshlrev_b32_e32 v44, 16, v102
	v_and_b32_e32 v45, 0xffff0000, v102
	v_lshlrev_b32_e32 v102, 16, v103
	s_waitcnt lgkmcnt(0)
	v_add_f32_e32 v0, v0, v63
	ds_bpermute_b32 v63, v85, v0
	v_and_b32_e32 v103, 0xffff0000, v103
	v_lshlrev_b32_e32 v120, 16, v104
	v_and_b32_e32 v121, 0xffff0000, v104
	v_lshlrev_b32_e32 v104, 16, v105
	s_waitcnt lgkmcnt(0)
	v_add_f32_e32 v0, v0, v63
	ds_bpermute_b32 v63, v86, v0
	v_and_b32_e32 v105, 0xffff0000, v105
	s_waitcnt vmcnt(1)
	v_lshlrev_b32_e32 v122, 16, v106
	v_and_b32_e32 v123, 0xffff0000, v106
	v_lshlrev_b32_e32 v106, 16, v107
	s_waitcnt lgkmcnt(0)
	v_add_f32_e32 v0, v0, v63
	ds_bpermute_b32 v63, v87, v0
	v_and_b32_e32 v107, 0xffff0000, v107
	v_lshlrev_b32_e32 v124, 16, v108
	v_and_b32_e32 v125, 0xffff0000, v108
	v_lshlrev_b32_e32 v108, 16, v109
	s_waitcnt lgkmcnt(0)
	v_add_f32_e32 v0, v0, v63
	v_fmamk_f32 v0, v0, 0x3a000000, v223
	v_mul_f32_e32 v63, 0x4b800000, v0
	v_cmp_gt_f32_e64 s[36:37], s0, v0
	v_and_b32_e32 v109, 0xffff0000, v109
	s_waitcnt vmcnt(0)
; __device__ __forceinline__ size_t xoff(int row, int col) { return ((size_t)((row >> 8) * 32 + (col >> 6)) * 256 + (row & 255)) * 64 + (col & 63); }
; __device__ __forceinline__ u32x4 pack8(f32x4 v0, f32x4 v1) { u32x4 w; w.x = cvt_pk_bf16(v0[0], v0[1]); w.y = cvt_pk_bf16(v0[2], v0[3]); w.z = cvt_pk_bf16(v1[0], v1[1]); w.w = cvt_pk_bf16(v1[2], v1[3]); return w; }
; __device__ void norm_rows(const Params& p, int mode, float scale, const float* gpost) {
;     ...
;             const float rs = rsqrtf(ss * (1.0f / DM) + RMS_EPS) * scale;
; #pragma unroll
;             for (int c = 0; c < 4; ++c) { xv[2 * c] += yv[2 * c] * gq[2 * c] * rs; xv[2 * c + 1] += yv[2 * c + 1] * gq[2 * c + 1] * rs; }
;         }
;         if (mode == 2) {
; #pragma unroll
;             for (int c = 0; c < 4; ++c) { *(f32x4*)(p.out + (size_t)row * DM + (c * 64 + lane) * 8) = xv[2 * c]; *(f32x4*)(p.out + (size_t)row * DM + (c * 64 + lane) * 8 + 4) = xv[2 * c + 1]; }
;         } else {
;             float ss = 0.f;
; #pragma unroll
;             for (int c = 0; c < 8; ++c) ss += xv[c][0] * xv[c][0] + xv[c][1] * xv[c][1] + xv[c][2] * xv[c][2] + xv[c][3] * xv[c][3];
;             ss = wave_sum(ss);
; #pragma unroll
;             for (int c = 0; c < 4; ++c) *(u32x4*)(X + xoff(row, (c * 64 + lane) * 8)) = pack8(xv[2 * c], xv[2 * c + 1]);
;             if (lane == 0) RS[row] = rsqrtf(ss * (1.0f / DM) + RMS_EPS);
	v_lshlrev_b32_e32 v126, 16, v38
	v_cndmask_b32_e64 v0, v0, v63, s[36:37]
	v_rsq_f32_e32 v0, v0
	v_and_b32_e32 v127, 0xffff0000, v38
	v_lshlrev_b32_e32 v38, 16, v39
	v_and_b32_e32 v39, 0xffff0000, v39
	v_mul_f32_e32 v63, 0x45800000, v0
	v_cndmask_b32_e64 v0, v0, v63, s[36:37]
	v_mul_f32_e32 v0, 0.5, v0
	v_pk_fma_f32 v[32:33], v[32:33], v[0:1], v[34:35] op_sel_hi:[1,0,1]
	v_mov_b32_e32 v34, v75
	v_mov_b32_e32 v35, v79
	v_pk_mul_f32 v[14:15], v[14:15], v[34:35]
	v_mov_b32_e32 v34, v77
	v_mov_b32_e32 v35, v81
	v_pk_mul_f32 v[16:17], v[16:17], v[34:35]
	v_mov_b32_e32 v34, v95
	v_mov_b32_e32 v35, v97
	v_mov_b32_e32 v75, v78
	v_mov_b32_e32 v77, v80
	v_pk_mul_f32 v[6:7], v[6:7], v[34:35]
	v_mov_b32_e32 v34, v119
	v_mov_b32_e32 v35, v43
	v_mov_b32_e32 v95, v96
	v_mov_b32_e32 v119, v42
	v_lshlrev_b32_e32 v128, 16, v40
	v_and_b32_e32 v129, 0xffff0000, v40
	v_lshlrev_b32_e32 v40, 16, v41
	v_and_b32_e32 v41, 0xffff0000, v41
	v_pk_fma_f32 v[30:31], v[30:31], v[0:1], v[110:111] op_sel_hi:[1,0,1]
	v_pk_mul_f32 v[28:29], v[28:29], v[100:101]
	v_pk_fma_f32 v[26:27], v[26:27], v[0:1], v[112:113] op_sel_hi:[1,0,1]
	v_pk_mul_f32 v[22:23], v[22:23], v[72:73]
	v_pk_mul_f32 v[24:25], v[24:25], v[70:71]
	v_pk_mul_f32 v[18:19], v[18:19], v[68:69]
	v_pk_mul_f32 v[20:21], v[20:21], v[66:67]
	v_pk_mul_f32 v[10:11], v[10:11], v[74:75]
	v_pk_mul_f32 v[12:13], v[12:13], v[76:77]
	v_pk_mul_f32 v[8:9], v[8:9], v[34:35]
	v_pk_mul_f32 v[2:3], v[2:3], v[94:95]
	v_pk_mul_f32 v[4:5], v[4:5], v[118:119]
	v_pk_fma_f32 v[28:29], v[28:29], v[0:1], v[36:37] op_sel_hi:[1,0,1]
	v_pk_fma_f32 v[24:25], v[24:25], v[0:1], v[102:103] op_sel_hi:[1,0,1]
	v_pk_fma_f32 v[22:23], v[22:23], v[0:1], v[44:45] op_sel_hi:[1,0,1]
	v_pk_fma_f32 v[20:21], v[20:21], v[0:1], v[104:105] op_sel_hi:[1,0,1]
	v_pk_fma_f32 v[18:19], v[18:19], v[0:1], v[120:121] op_sel_hi:[1,0,1]
	v_pk_fma_f32 v[16:17], v[16:17], v[0:1], v[106:107] op_sel_hi:[1,0,1]
	v_pk_fma_f32 v[14:15], v[14:15], v[0:1], v[122:123] op_sel_hi:[1,0,1]
	v_pk_fma_f32 v[12:13], v[12:13], v[0:1], v[108:109] op_sel_hi:[1,0,1]
	v_pk_fma_f32 v[10:11], v[10:11], v[0:1], v[124:125] op_sel_hi:[1,0,1]
	v_pk_fma_f32 v[8:9], v[8:9], v[0:1], v[38:39] op_sel_hi:[1,0,1]
	v_pk_fma_f32 v[34:35], v[6:7], v[0:1], v[126:127] op_sel_hi:[1,0,1]
	v_pk_fma_f32 v[36:37], v[4:5], v[0:1], v[40:41] op_sel_hi:[1,0,1]
	v_pk_fma_f32 v[38:39], v[2:3], v[0:1], v[128:129] op_sel_hi:[1,0,1]
	v_mul_f32_e32 v0, v31, v31
	v_mul_f32_e32 v2, v27, v27
	v_fmac_f32_e32 v0, v30, v30
	v_fmac_f32_e32 v2, v26, v26
	v_fmac_f32_e32 v0, v32, v32
	v_fmac_f32_e32 v2, v28, v28
	v_fmac_f32_e32 v0, v33, v33
	v_fmac_f32_e32 v2, v29, v29
	v_add_f32_e32 v0, v0, v2
	v_mul_f32_e32 v2, v23, v23
	v_fmac_f32_e32 v2, v22, v22
	v_fmac_f32_e32 v2, v24, v24
	v_fmac_f32_e32 v2, v25, v25
	v_add_f32_e32 v0, v2, v0
	v_mul_f32_e32 v2, v19, v19
	v_fmac_f32_e32 v2, v18, v18
	v_fmac_f32_e32 v2, v20, v20
	v_fmac_f32_e32 v2, v21, v21
	v_add_f32_e32 v0, v2, v0
	v_mul_f32_e32 v2, v15, v15
	v_fmac_f32_e32 v2, v14, v14
	v_fmac_f32_e32 v2, v16, v16
	v_fmac_f32_e32 v2, v17, v17
	v_add_f32_e32 v0, v2, v0
	v_mul_f32_e32 v2, v11, v11
	v_fmac_f32_e32 v2, v10, v10
	v_fmac_f32_e32 v2, v12, v12
	v_fmac_f32_e32 v2, v13, v13
	v_add_f32_e32 v0, v2, v0
	v_mul_f32_e32 v2, v35, v35
	v_fmac_f32_e32 v2, v34, v34
	v_fmac_f32_e32 v2, v8, v8
	v_fmac_f32_e32 v2, v9, v9
	v_add_f32_e32 v0, v2, v0
	v_mul_f32_e32 v2, v39, v39
	v_fmac_f32_e32 v2, v38, v38
	v_fmac_f32_e32 v2, v36, v36
	v_fmac_f32_e32 v2, v37, v37
	v_add_f32_e32 v0, v2, v0
	ds_bpermute_b32 v2, v82, v0
	v_cvt_pk_bf16_f32 v6, v26, v27
	v_cvt_pk_bf16_f32 v4, v30, v31
	v_cvt_pk_bf16_f32 v5, v32, v33
	v_cvt_pk_bf16_f32 v7, v28, v29
	s_waitcnt lgkmcnt(0)
	v_add_f32_e32 v0, v0, v2
	ds_bpermute_b32 v2, v83, v0
	global_store_dwordx4 v[64:65], v[4:7], off nt
	s_waitcnt lgkmcnt(0)
	v_add_f32_e32 v0, v0, v2
	ds_bpermute_b32 v2, v84, v0
	v_cvt_pk_bf16_f32 v6, v18, v19
	v_or_b32_e32 v18, 8, v62
	v_ashrrev_i32_e32 v19, 31, v18
	v_lshlrev_b64 v[18:19], 15, v[18:19]
	s_waitcnt lgkmcnt(0)
	v_add_f32_e32 v0, v0, v2
	ds_bpermute_b32 v2, v85, v0
	v_lshl_add_u64 v[18:19], v[60:61], 0, v[18:19]
	v_cvt_pk_bf16_f32 v4, v22, v23
	v_cvt_pk_bf16_f32 v5, v24, v25
	v_cvt_pk_bf16_f32 v7, v20, v21
	s_waitcnt lgkmcnt(0)
	v_add_f32_e32 v0, v0, v2
	ds_bpermute_b32 v2, v86, v0
	global_store_dwordx4 v[18:19], v[4:7], off nt
	s_waitcnt lgkmcnt(0)
	v_add_f32_e32 v0, v0, v2
	v_cvt_pk_bf16_f32 v6, v10, v11
	v_or_b32_e32 v10, 16, v62
	v_ashrrev_i32_e32 v11, 31, v10
	v_lshlrev_b64 v[10:11], 15, v[10:11]
	ds_bpermute_b32 v2, v87, v0
	v_cvt_pk_bf16_f32 v5, v16, v17
	v_lshl_add_u64 v[10:11], v[60:61], 0, v[10:11]
	v_cvt_pk_bf16_f32 v4, v14, v15
	v_cvt_pk_bf16_f32 v7, v12, v13
	global_store_dwordx4 v[10:11], v[4:7], off nt
	s_nop 1
	v_cvt_pk_bf16_f32 v5, v8, v9
	v_or_b32_e32 v8, 24, v62
	v_ashrrev_i32_e32 v9, 31, v8
	v_lshlrev_b64 v[8:9], 15, v[8:9]
	v_lshl_add_u64 v[8:9], v[60:61], 0, v[8:9]
	v_cvt_pk_bf16_f32 v4, v34, v35
	v_cvt_pk_bf16_f32 v6, v38, v39
	v_cvt_pk_bf16_f32 v7, v36, v37
	global_store_dwordx4 v[8:9], v[4:7], off nt
	s_and_saveexec_b64 s[0:1], vcc
	s_cbranch_execz .LBB0_786
	s_waitcnt lgkmcnt(0)
	v_add_f32_e32 v0, v0, v2
	v_fmamk_f32 v0, v0, 0x3a000000, v223
	s_mov_b32 s2, 0x800000
	v_mul_f32_e32 v2, 0x4b800000, v0
	v_cmp_gt_f32_e64 s[36:37], s2, v0
	v_readlane_b32 s2, v254, 22
	v_readlane_b32 s3, v254, 23
	v_cndmask_b32_e64 v0, v0, v2, s[36:37]
	v_rsq_f32_e32 v0, v0
	s_nop 0
	v_mul_f32_e32 v2, 0x45800000, v0
	v_cndmask_b32_e64 v0, v0, v2, s[36:37]
	v_lshl_add_u64 v[2:3], v[46:47], 2, s[2:3]
	global_store_dword v[2:3], v0, off
	s_branch .LBB0_786

; __device__ __forceinline__ size_t xoff(int row, int col) { return ((size_t)((row >> 8) * 32 + (col >> 6)) * 256 + (row & 255)) * 64 + (col & 63); }
; __device__ __forceinline__ void unpack8(u32x4 w, f32x4& v0, f32x4& v1) { v0 = (f32x4){bflo(w.x), bfhi(w.x), bflo(w.y), bfhi(w.y)}; v1 = (f32x4){bflo(w.z), bfhi(w.z), bflo(w.w), bfhi(w.w)}; }
; __device__ void norm_rows(const Params& p, int mode, float scale, const float* gpost) {
;     ...
;             f32x4 yv[8]; float ss = 0.f; u32x4 xw[4], yw[4]; f32x4 gq[8];
; #pragma unroll
;             for (int c = 0; c < 4; ++c) { xw[c] = *(const u32x4*)(X + xoff(row, (c * 64 + lane) * 8)); yw[c] = *(const u32x4*)(Y + (size_t)row * DM + (c * 64 + lane) * 8); }
; #pragma unroll
;             for (int c = 0; c < 4; ++c) { gq[2 * c] = *(const f32x4*)(gpost + (c * 64 + lane) * 8); gq[2 * c + 1] = *(const f32x4*)(gpost + (c * 64 + lane) * 8 + 4); }
;             asm volatile("" ::: "memory");
; #pragma unroll
;             for (int c = 0; c < 4; ++c) { unpack8(xw[c], xv[2 * c], xv[2 * c + 1]); unpack8(yw[c], yv[2 * c], yv[2 * c + 1]); }
; #pragma unroll
;             for (int c = 0; c < 8; ++c) ss += yv[c][0] * yv[c][0] + yv[c][1] * yv[c][1] + yv[c][2] * yv[c][2] + yv[c][3] * yv[c][3];
;             ss = wave_sum(ss);
;             const float rs = rsqrtf(ss * (1.0f / DM) + RMS_EPS) * scale;
.LBB0_1013:
	v_ashrrev_i32_e32 v47, 31, v46
	v_lshlrev_b64 v[2:3], 12, v[46:47]
	v_lshl_add_u64 v[2:3], v[58:59], 0, v[2:3]
	global_load_dwordx4 v[80:83], v[2:3], off offset:1024
	global_load_dwordx4 v[86:89], v[2:3], off offset:2048
	v_ashrrev_i32_e32 v0, 3, v46
	v_and_b32_e32 v39, 0xffffffe0, v0
	v_and_b32_e32 v4, 0x3fc0, v100
	v_or_b32_e32 v68, v39, v96
	v_lshlrev_b32_e32 v0, 1, v4
	v_ashrrev_i32_e32 v69, 31, v68
	v_lshl_add_u64 v[66:67], v[48:49], 0, v[0:1]
	v_lshlrev_b64 v[4:5], 15, v[68:69]
	v_lshl_add_u64 v[70:71], v[66:67], 0, v[4:5]
	global_load_dwordx4 v[42:45], v[2:3], off offset:3072
	s_waitcnt lgkmcnt(0)
	global_load_dwordx4 v[34:37], v[70:71], off
	global_load_dwordx4 v[102:105], v[2:3], off
	global_load_dwordx4 v[30:33], v[50:51], off offset:16
	global_load_dwordx4 v[22:25], v[50:51], off
	global_load_dwordx4 v[18:21], v[52:53], off offset:16
	global_load_dwordx4 v[26:29], v[52:53], off
	global_load_dwordx4 v[10:13], v[54:55], off offset:16
	global_load_dwordx4 v[14:17], v[54:55], off
	global_load_dwordx4 v[2:5], v[56:57], off offset:16
	global_load_dwordx4 v[6:9], v[56:57], off
	v_or_b32_e32 v38, v39, v97
	v_or_b32_e32 v40, v39, v98
	v_or_b32_e32 v72, v39, v99
	v_ashrrev_i32_e32 v39, 31, v38
	v_lshlrev_b64 v[38:39], 15, v[38:39]
	v_ashrrev_i32_e32 v41, 31, v40
	v_ashrrev_i32_e32 v73, 31, v72
	v_lshl_add_u64 v[38:39], v[66:67], 0, v[38:39]
	global_load_dwordx4 v[106:109], v[38:39], off
	v_lshlrev_b64 v[38:39], 15, v[40:41]
	v_lshlrev_b64 v[40:41], 15, v[72:73]
	v_lshl_add_u64 v[38:39], v[66:67], 0, v[38:39]
	v_lshl_add_u64 v[40:41], v[66:67], 0, v[40:41]
	global_load_dwordx4 v[110:113], v[38:39], off
	s_nop 0
	global_load_dwordx4 v[38:41], v[40:41], off
	s_mov_b32 s0, 0x800000
	s_waitcnt vmcnt(15)
	v_and_b32_e32 v79, 0xffff0000, v80
	v_lshlrev_b32_e32 v78, 16, v80
	v_and_b32_e32 v75, 0xffff0000, v82
	v_mul_f32_e32 v0, v79, v79
	s_waitcnt vmcnt(11)
	v_and_b32_e32 v121, 0xffff0000, v102
	v_and_b32_e32 v123, 0xffff0000, v104
	v_lshlrev_b32_e32 v120, 16, v102
	v_lshlrev_b32_e32 v122, 16, v104
	v_mul_f32_e32 v63, v121, v121
	v_mul_f32_e32 v65, v123, v123
	v_lshlrev_b32_e32 v102, 16, v103
	v_lshlrev_b32_e32 v104, 16, v105
	v_fmac_f32_e32 v63, v120, v120
	v_fmac_f32_e32 v65, v122, v122
	v_lshlrev_b32_e32 v76, 16, v81
	v_lshlrev_b32_e32 v74, 16, v82
	v_and_b32_e32 v85, 0xffff0000, v86
	v_and_b32_e32 v84, 0xffff0000, v88
	v_mul_f32_e32 v61, v75, v75
	v_fmac_f32_e32 v0, v78, v78
	v_and_b32_e32 v103, 0xffff0000, v103
	v_and_b32_e32 v105, 0xffff0000, v105
	v_fmac_f32_e32 v63, v102, v102
	v_fmac_f32_e32 v65, v104, v104
	v_and_b32_e32 v77, 0xffff0000, v81
	v_lshlrev_b32_e32 v72, 16, v83
	v_lshlrev_b32_e32 v81, 16, v86
	v_lshlrev_b32_e32 v80, 16, v88
	v_pk_mul_f32 v[114:115], v[84:85], v[84:85]
	v_fmac_f32_e32 v61, v74, v74
	v_fmac_f32_e32 v0, v76, v76
	v_fmac_f32_e32 v63, v103, v103
	v_fmac_f32_e32 v65, v105, v105
	v_and_b32_e32 v73, 0xffff0000, v83
	v_lshlrev_b32_e32 v83, 16, v87
	v_lshlrev_b32_e32 v82, 16, v89
	v_pk_fma_f32 v[114:115], v[80:81], v[80:81], v[114:115]
	v_fmac_f32_e32 v61, v72, v72
	v_fmac_f32_e32 v0, v77, v77
	v_add_f32_e32 v63, v63, v65
	v_and_b32_e32 v87, 0xffff0000, v87
	v_and_b32_e32 v86, 0xffff0000, v89
	v_pk_fma_f32 v[114:115], v[82:83], v[82:83], v[114:115]
	v_fmac_f32_e32 v61, v73, v73
	v_add_f32_e32 v0, v63, v0
	v_pk_fma_f32 v[114:115], v[86:87], v[86:87], v[114:115]
	v_add_f32_e32 v0, v61, v0
	v_add_f32_e32 v0, v0, v115
	v_add_f32_e32 v0, v114, v0
	v_and_b32_e32 v115, 0xffff0000, v42
	v_and_b32_e32 v114, 0xffff0000, v44
	v_lshlrev_b32_e32 v89, 16, v42
	v_lshlrev_b32_e32 v88, 16, v44
	v_lshlrev_b32_e32 v124, 16, v45
	v_and_b32_e32 v42, 0xffff0000, v45
	v_pk_mul_f32 v[44:45], v[114:115], v[114:115]
	v_lshlrev_b32_e32 v125, 16, v43
	v_pk_fma_f32 v[44:45], v[88:89], v[88:89], v[44:45]
	v_and_b32_e32 v43, 0xffff0000, v43
	v_pk_fma_f32 v[44:45], v[124:125], v[124:125], v[44:45]
	v_lshlrev_b32_e32 v116, 16, v34
	v_pk_fma_f32 v[44:45], v[42:43], v[42:43], v[44:45]
	v_and_b32_e32 v117, 0xffff0000, v34
	v_add_f32_e32 v0, v0, v45
	v_add_f32_e32 v0, v44, v0
	ds_bpermute_b32 v45, v90, v0
	v_lshlrev_b32_e32 v34, 16, v35
	v_and_b32_e32 v35, 0xffff0000, v35
	s_waitcnt vmcnt(9)
	v_pk_mul_f32 v[24:25], v[24:25], v[102:103]
	v_lshlrev_b32_e32 v118, 16, v36
	s_waitcnt lgkmcnt(0)
	v_add_f32_e32 v0, v0, v45
	ds_bpermute_b32 v61, v91, v0
	v_and_b32_e32 v119, 0xffff0000, v36
	v_lshlrev_b32_e32 v36, 16, v37
	v_and_b32_e32 v37, 0xffff0000, v37
	s_waitcnt vmcnt(2)
	v_lshlrev_b32_e32 v44, 16, v106
	s_waitcnt lgkmcnt(0)
	v_add_f32_e32 v0, v0, v61
	ds_bpermute_b32 v61, v92, v0
	v_and_b32_e32 v45, 0xffff0000, v106
	v_lshlrev_b32_e32 v106, 16, v107
	v_and_b32_e32 v107, 0xffff0000, v107
	v_lshlrev_b32_e32 v126, 16, v108
	s_waitcnt lgkmcnt(0)
	v_add_f32_e32 v0, v0, v61
	ds_bpermute_b32 v61, v93, v0
	v_and_b32_e32 v127, 0xffff0000, v108
	v_lshlrev_b32_e32 v108, 16, v109
	v_and_b32_e32 v109, 0xffff0000, v109
	s_waitcnt vmcnt(1)
	v_lshlrev_b32_e32 v128, 16, v110
	s_waitcnt lgkmcnt(0)
	v_add_f32_e32 v0, v0, v61
	ds_bpermute_b32 v61, v94, v0
	v_and_b32_e32 v129, 0xffff0000, v110
	v_lshlrev_b32_e32 v110, 16, v111
	v_and_b32_e32 v111, 0xffff0000, v111
	v_lshlrev_b32_e32 v130, 16, v112
	s_waitcnt lgkmcnt(0)
	v_add_f32_e32 v0, v0, v61
	ds_bpermute_b32 v61, v95, v0
	v_and_b32_e32 v131, 0xffff0000, v112
	v_lshlrev_b32_e32 v112, 16, v113
	v_and_b32_e32 v113, 0xffff0000, v113
	s_waitcnt vmcnt(0)
	v_lshlrev_b32_e32 v132, 16, v38
	s_waitcnt lgkmcnt(0)
; __device__ __forceinline__ size_t xoff(int row, int col) { return ((size_t)((row >> 8) * 32 + (col >> 6)) * 256 + (row & 255)) * 64 + (col & 63); }
; __device__ __forceinline__ u32x4 pack8(f32x4 v0, f32x4 v1) { u32x4 w; w.x = cvt_pk_bf16(v0[0], v0[1]); w.y = cvt_pk_bf16(v0[2], v0[3]); w.z = cvt_pk_bf16(v1[0], v1[1]); w.w = cvt_pk_bf16(v1[2], v1[3]); return w; }
; __device__ void norm_rows(const Params& p, int mode, float scale, const float* gpost) {
;     ...
;             const float rs = rsqrtf(ss * (1.0f / DM) + RMS_EPS) * scale;
; #pragma unroll
;             for (int c = 0; c < 4; ++c) { xv[2 * c] += yv[2 * c] * gq[2 * c] * rs; xv[2 * c + 1] += yv[2 * c + 1] * gq[2 * c + 1] * rs; }
;         }
;         if (mode == 2) {
; #pragma unroll
;             for (int c = 0; c < 4; ++c) { *(f32x4*)(p.out + (size_t)row * DM + (c * 64 + lane) * 8) = xv[2 * c]; *(f32x4*)(p.out + (size_t)row * DM + (c * 64 + lane) * 8 + 4) = xv[2 * c + 1]; }
;         } else {
;             float ss = 0.f;
; #pragma unroll
;             for (int c = 0; c < 8; ++c) ss += xv[c][0] * xv[c][0] + xv[c][1] * xv[c][1] + xv[c][2] * xv[c][2] + xv[c][3] * xv[c][3];
;             ss = wave_sum(ss);
; #pragma unroll
;             for (int c = 0; c < 4; ++c) *(u32x4*)(X + xoff(row, (c * 64 + lane) * 8)) = pack8(xv[2 * c], xv[2 * c + 1]);
;             if (lane == 0) RS[row] = rsqrtf(ss * (1.0f / DM) + RMS_EPS);
	v_add_f32_e32 v0, v0, v61
	v_fmamk_f32 v0, v0, 0x3a000000, v223
	v_mul_f32_e32 v61, 0x4b800000, v0
	v_cmp_gt_f32_e32 vcc, s0, v0
	v_and_b32_e32 v133, 0xffff0000, v38
	v_lshlrev_b32_e32 v38, 16, v39
	v_cndmask_b32_e32 v0, v0, v61, vcc
	v_rsq_f32_e32 v0, v0
	v_and_b32_e32 v39, 0xffff0000, v39
	v_lshlrev_b32_e32 v134, 16, v40
	v_and_b32_e32 v135, 0xffff0000, v40
	v_mul_f32_e32 v61, 0x45800000, v0
	v_cndmask_b32_e32 v0, v0, v61, vcc
	v_mul_f32_e32 v0, 0.5, v0
	v_pk_fma_f32 v[24:25], v[24:25], v[0:1], v[34:35] op_sel_hi:[1,0,1]
	v_mov_b32_e32 v34, v81
	v_mov_b32_e32 v35, v85
	v_pk_mul_f32 v[14:15], v[14:15], v[34:35]
	v_mov_b32_e32 v34, v83
	v_mov_b32_e32 v35, v87
	v_pk_mul_f32 v[16:17], v[16:17], v[34:35]
	v_mov_b32_e32 v34, v89
	v_mov_b32_e32 v35, v115
	v_mov_b32_e32 v81, v84
	v_mov_b32_e32 v83, v86
	v_pk_mul_f32 v[6:7], v[6:7], v[34:35]
	v_mov_b32_e32 v34, v125
	v_mov_b32_e32 v35, v43
	v_mov_b32_e32 v89, v114
	v_mov_b32_e32 v125, v42
	v_lshlrev_b32_e32 v40, 16, v41
	v_and_b32_e32 v41, 0xffff0000, v41
	v_pk_mul_f32 v[22:23], v[22:23], v[120:121]
	v_pk_mul_f32 v[30:31], v[30:31], v[122:123]
	v_pk_mul_f32 v[32:33], v[32:33], v[104:105]
	v_pk_mul_f32 v[26:27], v[26:27], v[78:79]
	v_pk_mul_f32 v[28:29], v[28:29], v[76:77]
	v_pk_mul_f32 v[18:19], v[18:19], v[74:75]
	v_pk_mul_f32 v[20:21], v[20:21], v[72:73]
	v_pk_mul_f32 v[10:11], v[10:11], v[80:81]
	v_pk_mul_f32 v[12:13], v[12:13], v[82:83]
	v_pk_mul_f32 v[8:9], v[8:9], v[34:35]
	v_pk_mul_f32 v[2:3], v[2:3], v[88:89]
	v_pk_mul_f32 v[4:5], v[4:5], v[124:125]
	v_pk_fma_f32 v[22:23], v[22:23], v[0:1], v[116:117] op_sel_hi:[1,0,1]
	v_pk_fma_f32 v[32:33], v[32:33], v[0:1], v[36:37] op_sel_hi:[1,0,1]
	v_pk_fma_f32 v[30:31], v[30:31], v[0:1], v[118:119] op_sel_hi:[1,0,1]
	v_pk_fma_f32 v[28:29], v[28:29], v[0:1], v[106:107] op_sel_hi:[1,0,1]
	v_pk_fma_f32 v[26:27], v[26:27], v[0:1], v[44:45] op_sel_hi:[1,0,1]
	v_pk_fma_f32 v[20:21], v[20:21], v[0:1], v[108:109] op_sel_hi:[1,0,1]
	v_pk_fma_f32 v[18:19], v[18:19], v[0:1], v[126:127] op_sel_hi:[1,0,1]
	v_pk_fma_f32 v[16:17], v[16:17], v[0:1], v[110:111] op_sel_hi:[1,0,1]
	v_pk_fma_f32 v[14:15], v[14:15], v[0:1], v[128:129] op_sel_hi:[1,0,1]
	v_pk_fma_f32 v[12:13], v[12:13], v[0:1], v[112:113] op_sel_hi:[1,0,1]
	v_pk_fma_f32 v[10:11], v[10:11], v[0:1], v[130:131] op_sel_hi:[1,0,1]
	v_pk_fma_f32 v[8:9], v[8:9], v[0:1], v[38:39] op_sel_hi:[1,0,1]
	v_pk_fma_f32 v[6:7], v[6:7], v[0:1], v[132:133] op_sel_hi:[1,0,1]
	v_pk_fma_f32 v[4:5], v[4:5], v[0:1], v[40:41] op_sel_hi:[1,0,1]
	v_pk_fma_f32 v[2:3], v[2:3], v[0:1], v[134:135] op_sel_hi:[1,0,1]
	s_andn2_b64 vcc, exec, s[22:23]
	s_mov_b64 s[0:1], -1
	s_cbranch_vccnz .LBB0_1017
	v_mul_f32_e32 v0, v23, v23
	v_mul_f32_e32 v34, v31, v31
	v_fmac_f32_e32 v0, v22, v22
	v_fmac_f32_e32 v34, v30, v30
	v_fmac_f32_e32 v0, v24, v24
	v_fmac_f32_e32 v34, v32, v32
	v_fmac_f32_e32 v0, v25, v25
	v_fmac_f32_e32 v34, v33, v33
	v_add_f32_e32 v0, v0, v34
	v_mul_f32_e32 v34, v27, v27
	v_fmac_f32_e32 v34, v26, v26
	v_fmac_f32_e32 v34, v28, v28
	v_fmac_f32_e32 v34, v29, v29
	v_add_f32_e32 v0, v34, v0
	v_mul_f32_e32 v34, v19, v19
	v_fmac_f32_e32 v34, v18, v18
	v_fmac_f32_e32 v34, v20, v20
	v_fmac_f32_e32 v34, v21, v21
	v_add_f32_e32 v0, v34, v0
	v_mul_f32_e32 v34, v15, v15
	v_fmac_f32_e32 v34, v14, v14
	v_fmac_f32_e32 v34, v16, v16
	v_fmac_f32_e32 v34, v17, v17
	v_add_f32_e32 v0, v34, v0
	v_mul_f32_e32 v34, v11, v11
	v_fmac_f32_e32 v34, v10, v10
	v_fmac_f32_e32 v34, v12, v12
	v_fmac_f32_e32 v34, v13, v13
	v_add_f32_e32 v0, v34, v0
	v_mul_f32_e32 v34, v7, v7
	v_fmac_f32_e32 v34, v6, v6
	v_fmac_f32_e32 v34, v8, v8
	v_fmac_f32_e32 v34, v9, v9
	v_add_f32_e32 v0, v34, v0
	v_mul_f32_e32 v34, v3, v3
	v_fmac_f32_e32 v34, v2, v2
	v_fmac_f32_e32 v34, v4, v4
	v_fmac_f32_e32 v34, v5, v5
	v_add_f32_e32 v0, v34, v0
	ds_bpermute_b32 v34, v90, v0
	v_or_b32_e32 v40, 8, v68
	v_ashrrev_i32_e32 v41, 31, v40
	v_lshlrev_b64 v[40:41], 15, v[40:41]
	v_cvt_pk_bf16_f32 v36, v22, v23
	s_waitcnt lgkmcnt(0)
	v_add_f32_e32 v0, v0, v34
	ds_bpermute_b32 v34, v91, v0
	v_cvt_pk_bf16_f32 v37, v24, v25
	v_cvt_pk_bf16_f32 v38, v30, v31
	v_cvt_pk_bf16_f32 v39, v32, v33
	v_lshl_add_u64 v[40:41], v[66:67], 0, v[40:41]
	s_waitcnt lgkmcnt(0)
	v_add_f32_e32 v0, v0, v34
	ds_bpermute_b32 v34, v92, v0
	global_store_dwordx4 v[70:71], v[36:39], off nt
	s_waitcnt lgkmcnt(0)
	v_add_f32_e32 v0, v0, v34
	ds_bpermute_b32 v34, v93, v0
	v_cvt_pk_bf16_f32 v36, v26, v27
	v_cvt_pk_bf16_f32 v37, v28, v29
	v_cvt_pk_bf16_f32 v38, v18, v19
	v_cvt_pk_bf16_f32 v39, v20, v21
	s_waitcnt lgkmcnt(0)
	v_add_f32_e32 v0, v0, v34
	ds_bpermute_b32 v34, v94, v0
	global_store_dwordx4 v[40:41], v[36:39], off nt
	v_or_b32_e32 v40, 16, v68
	v_ashrrev_i32_e32 v41, 31, v40
	v_lshlrev_b64 v[40:41], 15, v[40:41]
	s_waitcnt lgkmcnt(0)
	v_add_f32_e32 v0, v0, v34
	ds_bpermute_b32 v34, v95, v0
	v_lshl_add_u64 v[40:41], v[66:67], 0, v[40:41]
	v_cvt_pk_bf16_f32 v36, v14, v15
	v_cvt_pk_bf16_f32 v37, v16, v17
	v_cvt_pk_bf16_f32 v38, v10, v11
	v_cvt_pk_bf16_f32 v39, v12, v13
	global_store_dwordx4 v[40:41], v[36:39], off nt
	v_or_b32_e32 v40, 24, v68
	v_ashrrev_i32_e32 v41, 31, v40
	v_lshlrev_b64 v[40:41], 15, v[40:41]
	v_lshl_add_u64 v[40:41], v[66:67], 0, v[40:41]
	v_cvt_pk_bf16_f32 v36, v6, v7
	v_cvt_pk_bf16_f32 v37, v8, v9
	v_cvt_pk_bf16_f32 v38, v2, v3
	v_cvt_pk_bf16_f32 v39, v4, v5
	global_store_dwordx4 v[40:41], v[36:39], off nt
	s_and_saveexec_b64 s[0:1], s[36:37]
	s_cbranch_execz .LBB0_1016
	s_waitcnt lgkmcnt(0)
	v_add_f32_e32 v0, v0, v34
	v_fmamk_f32 v0, v0, 0x3a000000, v223
	s_mov_b32 s2, 0x800000
	v_mul_f32_e32 v34, 0x4b800000, v0
	v_cmp_gt_f32_e32 vcc, s2, v0
	v_readlane_b32 s2, v254, 22
	v_readlane_b32 s3, v254, 23
	v_cndmask_b32_e32 v0, v0, v34, vcc
	v_rsq_f32_e32 v0, v0
	s_nop 0
	v_mul_f32_e32 v34, 0x45800000, v0
	v_cndmask_b32_e32 v0, v0, v34, vcc
	v_lshl_add_u64 v[34:35], v[46:47], 2, s[2:3]
	global_store_dword v[34:35], v0, off
